# v054: v039 + K=256 loop-top drain hoisted + L2 warm-up of pooling-state rows before the sample pool prep
# baseline (speedup 1.0000x reference)
.LBB0_393:
	s_ashr_i32 s13, s12, 31
	s_lshl_b64 s[18:19], s[12:13], 17
	s_add_u32 s18, s45, s18
	s_addc_u32 s19, s46, s19
	s_and_b64 s[22:23], s[22:23], exec
	v_mov_b32_e32 v2, 0
	s_cselect_b32 s1, s19, s7
	s_cselect_b32 s13, s18, s6
	s_mov_b64 s[24:25], 0
	s_mov_b64 s[22:23], -1
	s_mov_b64 s[28:29], 0
	s_waitcnt lgkmcnt(0)
	v_mov_b32_e32 v3, v2
	v_mov_b32_e32 v4, v2
	v_mov_b32_e32 v5, v2
	v_mov_b32_e32 v6, v2
	v_mov_b32_e32 v7, v2
	v_mov_b32_e32 v8, v2
	v_mov_b32_e32 v9, v2
	v_mov_b32_e32 v18, v2
	v_mov_b32_e32 v19, v2
	v_mov_b32_e32 v20, v2
	v_mov_b32_e32 v21, v2
	v_mov_b32_e32 v22, v2
	v_mov_b32_e32 v23, v2
	v_mov_b32_e32 v24, v2
	v_mov_b32_e32 v25, v2
	v_mov_b32_e32 v34, v2
	v_mov_b32_e32 v35, v2
	v_mov_b32_e32 v36, v2
	v_mov_b32_e32 v37, v2
	v_mov_b32_e32 v38, v2
	v_mov_b32_e32 v39, v2
	v_mov_b32_e32 v40, v2
	v_mov_b32_e32 v41, v2
	v_mov_b32_e32 v50, v2
	v_mov_b32_e32 v51, v2
	v_mov_b32_e32 v52, v2
	v_mov_b32_e32 v53, v2
	v_mov_b32_e32 v54, v2
	v_mov_b32_e32 v55, v2
	v_mov_b32_e32 v56, v2
	v_mov_b32_e32 v57, v2
	v_mov_b32_e32 v10, v2
	v_mov_b32_e32 v11, v2
	v_mov_b32_e32 v12, v2
	v_mov_b32_e32 v13, v2
	v_mov_b32_e32 v14, v2
	v_mov_b32_e32 v15, v2
	v_mov_b32_e32 v16, v2
	v_mov_b32_e32 v17, v2
	v_mov_b32_e32 v26, v2
	v_mov_b32_e32 v27, v2
	v_mov_b32_e32 v28, v2
	v_mov_b32_e32 v29, v2
	v_mov_b32_e32 v30, v2
	v_mov_b32_e32 v31, v2
	v_mov_b32_e32 v32, v2
	v_mov_b32_e32 v33, v2
	v_mov_b32_e32 v42, v2
	v_mov_b32_e32 v43, v2
	v_mov_b32_e32 v44, v2
	v_mov_b32_e32 v45, v2
	v_mov_b32_e32 v46, v2
	v_mov_b32_e32 v47, v2
	v_mov_b32_e32 v48, v2
	v_mov_b32_e32 v49, v2
	v_mov_b32_e32 v58, v2
	v_mov_b32_e32 v59, v2
	v_mov_b32_e32 v60, v2
	v_mov_b32_e32 v61, v2
	v_mov_b32_e32 v62, v2
	v_mov_b32_e32 v63, v2
	v_mov_b32_e32 v64, v2
	v_mov_b32_e32 v65, v2
	v_mov_b32_e32 v66, v2
	v_mov_b32_e32 v67, v2
	v_mov_b32_e32 v68, v2
	v_mov_b32_e32 v69, v2
	v_mov_b32_e32 v70, v2
	v_mov_b32_e32 v71, v2
	v_mov_b32_e32 v72, v2
	v_mov_b32_e32 v73, v2
	v_mov_b32_e32 v82, v2
	v_mov_b32_e32 v83, v2
	v_mov_b32_e32 v84, v2
	v_mov_b32_e32 v85, v2
	v_mov_b32_e32 v86, v2
	v_mov_b32_e32 v87, v2
	v_mov_b32_e32 v88, v2
	v_mov_b32_e32 v89, v2
	v_mov_b32_e32 v98, v2
	v_mov_b32_e32 v99, v2
	v_mov_b32_e32 v100, v2
	v_mov_b32_e32 v101, v2
	v_mov_b32_e32 v102, v2
	v_mov_b32_e32 v103, v2
	v_mov_b32_e32 v104, v2
	v_mov_b32_e32 v105, v2
	v_mov_b32_e32 v114, v2
	v_mov_b32_e32 v115, v2
	v_mov_b32_e32 v116, v2
	v_mov_b32_e32 v117, v2
	v_mov_b32_e32 v118, v2
	v_mov_b32_e32 v119, v2
	v_mov_b32_e32 v120, v2
	v_mov_b32_e32 v121, v2
	v_mov_b32_e32 v74, v2
	v_mov_b32_e32 v75, v2
	v_mov_b32_e32 v76, v2
	v_mov_b32_e32 v77, v2
	v_mov_b32_e32 v78, v2
	v_mov_b32_e32 v79, v2
	v_mov_b32_e32 v80, v2
	v_mov_b32_e32 v81, v2
	v_mov_b32_e32 v90, v2
	v_mov_b32_e32 v91, v2
	v_mov_b32_e32 v92, v2
	v_mov_b32_e32 v93, v2
	v_mov_b32_e32 v94, v2
	v_mov_b32_e32 v95, v2
	v_mov_b32_e32 v96, v2
	v_mov_b32_e32 v97, v2
	v_mov_b32_e32 v106, v2
	v_mov_b32_e32 v107, v2
	v_mov_b32_e32 v108, v2
	v_mov_b32_e32 v109, v2
	v_mov_b32_e32 v110, v2
	v_mov_b32_e32 v111, v2
	v_mov_b32_e32 v112, v2
	v_mov_b32_e32 v113, v2
	v_mov_b32_e32 v122, v2
	v_mov_b32_e32 v123, v2
	v_mov_b32_e32 v124, v2
	v_mov_b32_e32 v125, v2
	v_mov_b32_e32 v126, v2
	v_mov_b32_e32 v127, v2
	v_mov_b32_e32 v128, v2
	v_mov_b32_e32 v129, v2
	s_waitcnt vmcnt(0)
.LBB0_394:
	s_add_u32 s34, s20, s24
	s_addc_u32 s35, s21, s25
	s_add_u32 s36, s34, 0x100
	s_addc_u32 s37, s35, 0
	s_and_b64 s[30:31], s[28:29], exec
	s_cselect_b32 s39, s15, s37
	s_cselect_b32 s38, s14, s36
	s_add_u32 s24, s6, s24
	s_addc_u32 s25, s7, s25
	s_add_u32 s30, s24, 0x100
	s_addc_u32 s31, s25, 0
	s_add_u32 s24, s38, 0x80
	s_addc_u32 s25, s39, 0
	s_and_b64 s[28:29], s[28:29], exec
	s_cselect_b32 s41, s1, s31
	s_cselect_b32 s40, s13, s30
	s_add_u32 s42, s34, 0x12080
	s_addc_u32 s43, s35, 0
	s_add_i32 s78, s63, s49
	s_add_i32 m0, s50, 0xc000
	s_add_i32 s79, s50, 0xe000
	s_add_i32 s77, s78, 0x2000
	s_add_u32 s36, s40, 0x10000
	s_addc_u32 s37, s41, 0
	s_add_i32 s75, s64, s49
	s_add_i32 s73, s75, 0x2000
	s_add_i32 s72, 0, 0x18000
	s_add_u32 s34, s38, 0x12000
	ds_read_b128 v[146:149], v140
	ds_read_b128 v[150:153], v140 offset:1024
	ds_read_b128 v[154:157], v140 offset:2048
	ds_read_b128 v[158:161], v140 offset:3072
	s_addc_u32 s35, s39, 0
	s_add_i32 s70, 0, 0x1c000
	s_add_u32 s30, s40, 0x80
	s_addc_u32 s31, s41, 0
	s_add_i32 s71, s72, s49
	s_add_i32 s69, s71, 0x2000
	s_add_u32 s28, s40, 0x10080
	s_addc_u32 s29, s41, 0
	s_add_i32 s76, s70, s49
	s_add_i32 s74, s76, 0x2000
	ds_read_b128 v[162:165], v141
	ds_read_b128 v[166:169], v141 offset:1024
	ds_read_b128 v[170:173], v141 offset:2048
	ds_read_b128 v[174:177], v141 offset:3072
	ds_read_b128 v[178:181], v141 offset:4096
	ds_read_b128 v[182:185], v141 offset:5120
	ds_read_b128 v[186:189], v141 offset:6144
	ds_read_b128 v[190:193], v141 offset:7168
	s_nop 0
	v_lshl_add_u64 v[194:195], s[42:43], 0, v[130:131]
	global_load_lds_dwordx4 v[194:195], off
	v_lshl_add_u64 v[194:195], s[42:43], 0, v[134:135]
	s_mov_b32 m0, s79
	s_nop 0
	global_load_lds_dwordx4 v[194:195], off
	s_waitcnt lgkmcnt(8)
	s_barrier
	s_waitcnt lgkmcnt(0)
	s_setprio 1
	s_waitcnt lgkmcnt(0)
	v_mfma_f32_16x16x32_bf16 v[126:129], v[146:149], v[162:165], v[126:129]
	v_mfma_f32_16x16x32_bf16 v[122:125], v[154:157], v[162:165], v[122:125]
	v_mfma_f32_16x16x32_bf16 v[110:113], v[146:149], v[170:173], v[110:113]
	v_mfma_f32_16x16x32_bf16 v[106:109], v[154:157], v[170:173], v[106:109]
	v_mfma_f32_16x16x32_bf16 v[94:97], v[146:149], v[178:181], v[94:97]
	v_mfma_f32_16x16x32_bf16 v[90:93], v[154:157], v[178:181], v[90:93]
	v_mfma_f32_16x16x32_bf16 v[78:81], v[146:149], v[186:189], v[78:81]
	v_mfma_f32_16x16x32_bf16 v[74:77], v[154:157], v[186:189], v[74:77]
	v_mfma_f32_16x16x32_bf16 v[126:129], v[150:153], v[166:169], v[126:129]
	v_mfma_f32_16x16x32_bf16 v[122:125], v[158:161], v[166:169], v[122:125]
	v_mfma_f32_16x16x32_bf16 v[110:113], v[150:153], v[174:177], v[110:113]
	v_mfma_f32_16x16x32_bf16 v[106:109], v[158:161], v[174:177], v[106:109]
	v_mfma_f32_16x16x32_bf16 v[94:97], v[150:153], v[182:185], v[94:97]
	v_mfma_f32_16x16x32_bf16 v[90:93], v[158:161], v[182:185], v[90:93]
	v_mfma_f32_16x16x32_bf16 v[78:81], v[150:153], v[190:193], v[78:81]
	v_mfma_f32_16x16x32_bf16 v[74:77], v[158:161], v[190:193], v[74:77]
	s_setprio 0
	s_barrier
	s_mov_b32 m0, s78
	ds_read_b128 v[194:197], v142
	ds_read_b128 v[198:201], v142 offset:1024
	ds_read_b128 v[202:205], v142 offset:2048
	ds_read_b128 v[206:209], v142 offset:3072
	s_nop 0
	v_lshl_add_u64 v[210:211], s[40:41], 0, v[132:133]
	global_load_lds_dwordx4 v[210:211], off
	v_lshl_add_u64 v[210:211], s[40:41], 0, v[136:137]
	s_mov_b32 m0, s77
	s_nop 0
	global_load_lds_dwordx4 v[210:211], off
	s_barrier
	s_waitcnt lgkmcnt(0)
	s_setprio 1
	s_waitcnt lgkmcnt(0)
	v_mfma_f32_16x16x32_bf16 v[118:121], v[194:197], v[162:165], v[118:121]
	v_mfma_f32_16x16x32_bf16 v[114:117], v[202:205], v[162:165], v[114:117]
	v_mfma_f32_16x16x32_bf16 v[102:105], v[194:197], v[170:173], v[102:105]
	v_mfma_f32_16x16x32_bf16 v[98:101], v[202:205], v[170:173], v[98:101]
	v_mfma_f32_16x16x32_bf16 v[86:89], v[194:197], v[178:181], v[86:89]
	v_mfma_f32_16x16x32_bf16 v[82:85], v[202:205], v[178:181], v[82:85]
	v_mfma_f32_16x16x32_bf16 v[70:73], v[194:197], v[186:189], v[70:73]
	v_mfma_f32_16x16x32_bf16 v[66:69], v[202:205], v[186:189], v[66:69]
	v_mfma_f32_16x16x32_bf16 v[118:121], v[198:201], v[166:169], v[118:121]
	v_mfma_f32_16x16x32_bf16 v[114:117], v[206:209], v[166:169], v[114:117]
	v_mfma_f32_16x16x32_bf16 v[102:105], v[198:201], v[174:177], v[102:105]
	v_mfma_f32_16x16x32_bf16 v[98:101], v[206:209], v[174:177], v[98:101]
	v_mfma_f32_16x16x32_bf16 v[86:89], v[198:201], v[182:185], v[86:89]
	v_mfma_f32_16x16x32_bf16 v[82:85], v[206:209], v[182:185], v[82:85]
	v_mfma_f32_16x16x32_bf16 v[70:73], v[198:201], v[190:193], v[70:73]
	v_mfma_f32_16x16x32_bf16 v[66:69], v[206:209], v[190:193], v[66:69]
	s_setprio 0
	s_mov_b32 m0, s50
	s_barrier
	ds_read_b128 v[162:165], v141 offset:16384
	ds_read_b128 v[166:169], v141 offset:17408
	ds_read_b128 v[170:173], v141 offset:18432
	ds_read_b128 v[174:177], v141 offset:19456
	ds_read_b128 v[178:181], v141 offset:20480
	ds_read_b128 v[182:185], v141 offset:21504
	ds_read_b128 v[186:189], v141 offset:22528
	ds_read_b128 v[190:193], v141 offset:23552
	s_nop 0
	v_lshl_add_u64 v[210:211], s[38:39], 0, v[130:131]
	global_load_lds_dwordx4 v[210:211], off
	v_lshl_add_u64 v[210:211], s[38:39], 0, v[134:135]
	s_mov_b32 m0, s51
	s_nop 0
	global_load_lds_dwordx4 v[210:211], off
	s_barrier
	s_waitcnt lgkmcnt(0)
	s_setprio 1
	s_waitcnt lgkmcnt(0)
	v_mfma_f32_16x16x32_bf16 v[62:65], v[146:149], v[162:165], v[62:65]
	v_mfma_f32_16x16x32_bf16 v[58:61], v[154:157], v[162:165], v[58:61]
	v_mfma_f32_16x16x32_bf16 v[46:49], v[146:149], v[170:173], v[46:49]
	v_mfma_f32_16x16x32_bf16 v[42:45], v[154:157], v[170:173], v[42:45]
	v_mfma_f32_16x16x32_bf16 v[30:33], v[146:149], v[178:181], v[30:33]
	v_mfma_f32_16x16x32_bf16 v[26:29], v[154:157], v[178:181], v[26:29]
	v_mfma_f32_16x16x32_bf16 v[14:17], v[146:149], v[186:189], v[14:17]
	v_mfma_f32_16x16x32_bf16 v[10:13], v[154:157], v[186:189], v[10:13]
	v_mfma_f32_16x16x32_bf16 v[62:65], v[150:153], v[166:169], v[62:65]
	v_mfma_f32_16x16x32_bf16 v[58:61], v[158:161], v[166:169], v[58:61]
	v_mfma_f32_16x16x32_bf16 v[46:49], v[150:153], v[174:177], v[46:49]
	v_mfma_f32_16x16x32_bf16 v[42:45], v[158:161], v[174:177], v[42:45]
	v_mfma_f32_16x16x32_bf16 v[30:33], v[150:153], v[182:185], v[30:33]
	v_mfma_f32_16x16x32_bf16 v[26:29], v[158:161], v[182:185], v[26:29]
	v_mfma_f32_16x16x32_bf16 v[14:17], v[150:153], v[190:193], v[14:17]
	v_mfma_f32_16x16x32_bf16 v[10:13], v[158:161], v[190:193], v[10:13]
	s_setprio 0
	s_barrier
	s_mov_b32 m0, s75
	s_nop 0
	v_lshl_add_u64 v[146:147], s[36:37], 0, v[132:133]
	global_load_lds_dwordx4 v[146:147], off
	v_lshl_add_u64 v[146:147], s[36:37], 0, v[136:137]
	s_mov_b32 m0, s73
	s_nop 0
	global_load_lds_dwordx4 v[146:147], off
	s_waitcnt vmcnt(6)
	s_barrier
	s_setprio 1
	v_mfma_f32_16x16x32_bf16 v[54:57], v[194:197], v[162:165], v[54:57]
	v_mfma_f32_16x16x32_bf16 v[50:53], v[202:205], v[162:165], v[50:53]
	v_mfma_f32_16x16x32_bf16 v[38:41], v[194:197], v[170:173], v[38:41]
	v_mfma_f32_16x16x32_bf16 v[34:37], v[202:205], v[170:173], v[34:37]
	v_mfma_f32_16x16x32_bf16 v[22:25], v[194:197], v[178:181], v[22:25]
	v_mfma_f32_16x16x32_bf16 v[18:21], v[202:205], v[178:181], v[18:21]
	v_mfma_f32_16x16x32_bf16 v[6:9], v[194:197], v[186:189], v[6:9]
	v_mfma_f32_16x16x32_bf16 v[2:5], v[202:205], v[186:189], v[2:5]
	v_mfma_f32_16x16x32_bf16 v[54:57], v[198:201], v[166:169], v[54:57]
	v_mfma_f32_16x16x32_bf16 v[50:53], v[206:209], v[166:169], v[50:53]
	v_mfma_f32_16x16x32_bf16 v[38:41], v[198:201], v[174:177], v[38:41]
	v_mfma_f32_16x16x32_bf16 v[34:37], v[206:209], v[174:177], v[34:37]
	v_mfma_f32_16x16x32_bf16 v[22:25], v[198:201], v[182:185], v[22:25]
	v_mfma_f32_16x16x32_bf16 v[18:21], v[206:209], v[182:185], v[18:21]
	v_mfma_f32_16x16x32_bf16 v[6:9], v[198:201], v[190:193], v[6:9]
	v_mfma_f32_16x16x32_bf16 v[2:5], v[206:209], v[190:193], v[2:5]
	s_setprio 0
	v_add_u32_e32 v138, s72, v1
	s_barrier
	ds_read_b128 v[146:149], v138
	ds_read_b128 v[150:153], v138 offset:1024
	ds_read_b128 v[154:157], v138 offset:2048
	ds_read_b128 v[158:161], v138 offset:3072
	s_mov_b32 m0, s52
	ds_read_b128 v[162:165], v141 offset:32768
	ds_read_b128 v[166:169], v141 offset:33792
	ds_read_b128 v[170:173], v141 offset:34816
	ds_read_b128 v[174:177], v141 offset:35840
	ds_read_b128 v[178:181], v141 offset:36864
	ds_read_b128 v[182:185], v141 offset:37888
	ds_read_b128 v[186:189], v141 offset:38912
	ds_read_b128 v[190:193], v141 offset:39936
	s_nop 0
	v_lshl_add_u64 v[194:195], s[34:35], 0, v[130:131]
	global_load_lds_dwordx4 v[194:195], off
	v_lshl_add_u64 v[194:195], s[34:35], 0, v[134:135]
	s_mov_b32 m0, s53
	s_nop 0
	global_load_lds_dwordx4 v[194:195], off
	s_waitcnt lgkmcnt(8)
	s_barrier
	s_waitcnt lgkmcnt(0)
	s_setprio 1
	s_waitcnt lgkmcnt(0)
	v_mfma_f32_16x16x32_bf16 v[126:129], v[146:149], v[162:165], v[126:129]
	v_mfma_f32_16x16x32_bf16 v[122:125], v[154:157], v[162:165], v[122:125]
	v_mfma_f32_16x16x32_bf16 v[110:113], v[146:149], v[170:173], v[110:113]
	v_mfma_f32_16x16x32_bf16 v[106:109], v[154:157], v[170:173], v[106:109]
	v_mfma_f32_16x16x32_bf16 v[94:97], v[146:149], v[178:181], v[94:97]
	v_mfma_f32_16x16x32_bf16 v[90:93], v[154:157], v[178:181], v[90:93]
	v_mfma_f32_16x16x32_bf16 v[78:81], v[146:149], v[186:189], v[78:81]
	v_mfma_f32_16x16x32_bf16 v[74:77], v[154:157], v[186:189], v[74:77]
	v_mfma_f32_16x16x32_bf16 v[126:129], v[150:153], v[166:169], v[126:129]
	v_mfma_f32_16x16x32_bf16 v[122:125], v[158:161], v[166:169], v[122:125]
	v_mfma_f32_16x16x32_bf16 v[110:113], v[150:153], v[174:177], v[110:113]
	v_mfma_f32_16x16x32_bf16 v[106:109], v[158:161], v[174:177], v[106:109]
	v_mfma_f32_16x16x32_bf16 v[94:97], v[150:153], v[182:185], v[94:97]
	v_mfma_f32_16x16x32_bf16 v[90:93], v[158:161], v[182:185], v[90:93]
	v_mfma_f32_16x16x32_bf16 v[78:81], v[150:153], v[190:193], v[78:81]
	v_mfma_f32_16x16x32_bf16 v[74:77], v[158:161], v[190:193], v[74:77]
	s_setprio 0
	s_barrier
	v_add_u32_e32 v138, s70, v1
	s_mov_b32 m0, s71
	ds_read_b128 v[194:197], v138
	ds_read_b128 v[198:201], v138 offset:1024
	ds_read_b128 v[202:205], v138 offset:2048
	ds_read_b128 v[206:209], v138 offset:3072
	s_nop 0
	v_lshl_add_u64 v[210:211], s[30:31], 0, v[132:133]
	global_load_lds_dwordx4 v[210:211], off
	v_lshl_add_u64 v[210:211], s[30:31], 0, v[136:137]
	s_mov_b32 m0, s69
	s_nop 0
	global_load_lds_dwordx4 v[210:211], off
	s_barrier
	s_waitcnt lgkmcnt(0)
	s_setprio 1
	s_waitcnt lgkmcnt(0)
	v_mfma_f32_16x16x32_bf16 v[118:121], v[194:197], v[162:165], v[118:121]
	v_mfma_f32_16x16x32_bf16 v[114:117], v[202:205], v[162:165], v[114:117]
	v_mfma_f32_16x16x32_bf16 v[102:105], v[194:197], v[170:173], v[102:105]
	v_mfma_f32_16x16x32_bf16 v[98:101], v[202:205], v[170:173], v[98:101]
	v_mfma_f32_16x16x32_bf16 v[86:89], v[194:197], v[178:181], v[86:89]
	v_mfma_f32_16x16x32_bf16 v[82:85], v[202:205], v[178:181], v[82:85]
	v_mfma_f32_16x16x32_bf16 v[70:73], v[194:197], v[186:189], v[70:73]
	v_mfma_f32_16x16x32_bf16 v[66:69], v[202:205], v[186:189], v[66:69]
	v_mfma_f32_16x16x32_bf16 v[118:121], v[198:201], v[166:169], v[118:121]
	v_mfma_f32_16x16x32_bf16 v[114:117], v[206:209], v[166:169], v[114:117]
	v_mfma_f32_16x16x32_bf16 v[102:105], v[198:201], v[174:177], v[102:105]
	v_mfma_f32_16x16x32_bf16 v[98:101], v[206:209], v[174:177], v[98:101]
	v_mfma_f32_16x16x32_bf16 v[86:89], v[198:201], v[182:185], v[86:89]
	v_mfma_f32_16x16x32_bf16 v[82:85], v[206:209], v[182:185], v[82:85]
	v_mfma_f32_16x16x32_bf16 v[70:73], v[198:201], v[190:193], v[70:73]
	v_mfma_f32_16x16x32_bf16 v[66:69], v[206:209], v[190:193], v[66:69]
	s_setprio 0
	s_mov_b32 m0, s58
	s_barrier
	ds_read_b128 v[162:165], v141 offset:49152
	ds_read_b128 v[166:169], v141 offset:50176
	ds_read_b128 v[170:173], v141 offset:51200
	ds_read_b128 v[174:177], v141 offset:52224
	ds_read_b128 v[178:181], v141 offset:53248
	ds_read_b128 v[182:185], v141 offset:54272
	ds_read_b128 v[186:189], v141 offset:55296
	ds_read_b128 v[190:193], v141 offset:56320
	s_nop 0
	v_lshl_add_u64 v[210:211], s[24:25], 0, v[130:131]
	global_load_lds_dwordx4 v[210:211], off
	v_lshl_add_u64 v[210:211], s[24:25], 0, v[134:135]
	s_mov_b32 m0, s59
	s_nop 0
	global_load_lds_dwordx4 v[210:211], off
	s_barrier
	s_waitcnt lgkmcnt(0)
	s_setprio 1
	s_waitcnt lgkmcnt(0)
	v_mfma_f32_16x16x32_bf16 v[62:65], v[146:149], v[162:165], v[62:65]
	v_mfma_f32_16x16x32_bf16 v[58:61], v[154:157], v[162:165], v[58:61]
	v_mfma_f32_16x16x32_bf16 v[46:49], v[146:149], v[170:173], v[46:49]
	v_mfma_f32_16x16x32_bf16 v[42:45], v[154:157], v[170:173], v[42:45]
	v_mfma_f32_16x16x32_bf16 v[30:33], v[146:149], v[178:181], v[30:33]
	v_mfma_f32_16x16x32_bf16 v[26:29], v[154:157], v[178:181], v[26:29]
	v_mfma_f32_16x16x32_bf16 v[14:17], v[146:149], v[186:189], v[14:17]
	v_mfma_f32_16x16x32_bf16 v[10:13], v[154:157], v[186:189], v[10:13]
	v_mfma_f32_16x16x32_bf16 v[62:65], v[150:153], v[166:169], v[62:65]
	v_mfma_f32_16x16x32_bf16 v[58:61], v[158:161], v[166:169], v[58:61]
	v_mfma_f32_16x16x32_bf16 v[46:49], v[150:153], v[174:177], v[46:49]
	v_mfma_f32_16x16x32_bf16 v[42:45], v[158:161], v[174:177], v[42:45]
	v_mfma_f32_16x16x32_bf16 v[30:33], v[150:153], v[182:185], v[30:33]
	v_mfma_f32_16x16x32_bf16 v[26:29], v[158:161], v[182:185], v[26:29]
	v_mfma_f32_16x16x32_bf16 v[14:17], v[150:153], v[190:193], v[14:17]
	v_mfma_f32_16x16x32_bf16 v[10:13], v[158:161], v[190:193], v[10:13]
	s_setprio 0
	s_barrier
	s_mov_b32 m0, s76
	s_nop 0
	v_lshl_add_u64 v[146:147], s[28:29], 0, v[132:133]
	global_load_lds_dwordx4 v[146:147], off
	v_lshl_add_u64 v[146:147], s[28:29], 0, v[136:137]
	s_mov_b32 m0, s74
	s_nop 0
	global_load_lds_dwordx4 v[146:147], off
	s_waitcnt vmcnt(6)
	s_barrier
	s_setprio 1
	v_mfma_f32_16x16x32_bf16 v[54:57], v[194:197], v[162:165], v[54:57]
	v_mfma_f32_16x16x32_bf16 v[50:53], v[202:205], v[162:165], v[50:53]
	v_mfma_f32_16x16x32_bf16 v[38:41], v[194:197], v[170:173], v[38:41]
	v_mfma_f32_16x16x32_bf16 v[34:37], v[202:205], v[170:173], v[34:37]
	v_mfma_f32_16x16x32_bf16 v[22:25], v[194:197], v[178:181], v[22:25]
	v_mfma_f32_16x16x32_bf16 v[18:21], v[202:205], v[178:181], v[18:21]
	v_mfma_f32_16x16x32_bf16 v[6:9], v[194:197], v[186:189], v[6:9]
	v_mfma_f32_16x16x32_bf16 v[2:5], v[202:205], v[186:189], v[2:5]
	v_mfma_f32_16x16x32_bf16 v[54:57], v[198:201], v[166:169], v[54:57]
	v_mfma_f32_16x16x32_bf16 v[50:53], v[206:209], v[166:169], v[50:53]
	v_mfma_f32_16x16x32_bf16 v[38:41], v[198:201], v[174:177], v[38:41]
	v_mfma_f32_16x16x32_bf16 v[34:37], v[206:209], v[174:177], v[34:37]
	v_mfma_f32_16x16x32_bf16 v[22:25], v[198:201], v[182:185], v[22:25]
	v_mfma_f32_16x16x32_bf16 v[18:21], v[206:209], v[182:185], v[18:21]
	v_mfma_f32_16x16x32_bf16 v[6:9], v[198:201], v[190:193], v[6:9]
	v_mfma_f32_16x16x32_bf16 v[2:5], v[206:209], v[190:193], v[2:5]
	s_setprio 0
	s_andn2_b64 vcc, exec, s[22:23]
	s_mov_b64 s[28:29], -1
	s_mov_b64 s[22:23], 0
	s_mov_b64 s[24:25], 0x100
	s_barrier
	s_cbranch_vccz .LBB0_394
	v_mov_b32_e32 v154, v0
	s_ashr_i32 s1, s0, 31
	v_readfirstlane_b32 s6, v154
	s_bfe_u32 s13, s6, 0x20006
	s_ashr_i32 s6, s6, 2
	s_andn2_b32 s6, s6, 63
	s_ashr_i32 s7, s6, 31
	s_lshl_b64 s[20:21], s[0:1], 10
	s_add_u32 s22, s54, s20
	s_addc_u32 s23, s55, s21
	s_lshl_b64 s[20:21], s[6:7], 2
	v_and_b32_e32 v145, 15, v154
	s_add_u32 s20, s22, s20
	s_addc_u32 s21, s23, s21
	v_lshlrev_b32_e32 v138, 2, v145
	global_load_dword v153, v138, s[20:21] offset:64
	global_load_dword v152, v138, s[20:21] offset:128
	global_load_dword v151, v138, s[20:21] offset:192
	global_load_dword v150, v138, s[20:21] offset:512
	global_load_dword v149, v138, s[20:21] offset:576
	global_load_dword v148, v138, s[20:21] offset:640
	global_load_dword v147, v138, s[20:21] offset:704
	v_mul_f32_e32 v127, v127, v127
	v_mul_f32_e32 v123, v123, v123
	v_mul_f32_e32 v119, v119, v119
	v_mul_f32_e32 v115, v115, v115
	v_fmac_f32_e32 v127, v126, v126
	v_mul_f32_e32 v126, v129, v129
	v_fmac_f32_e32 v123, v122, v122
	v_mul_f32_e32 v122, v125, v125
	v_fmac_f32_e32 v119, v118, v118
	v_mul_f32_e32 v118, v121, v121
	v_fmac_f32_e32 v115, v114, v114
	v_mul_f32_e32 v114, v117, v117
	v_fmac_f32_e32 v126, v128, v128
	v_fmac_f32_e32 v122, v124, v124
	v_fmac_f32_e32 v118, v120, v120
	v_fmac_f32_e32 v114, v116, v116
	v_add_f32_e32 v126, v127, v126
	v_add_f32_e32 v122, v123, v122
	v_add_f32_e32 v118, v119, v118
	v_add_f32_e32 v114, v115, v114
	v_add_f32_e32 v122, v126, v122
	v_add_f32_e32 v114, v118, v114
	v_add_f32_e32 v115, v122, v114
	ds_swizzle_b32 v116, v115 offset:swizzle(SWAP,16)
	v_and_b32_e32 v156, 64, v143
	v_xor_b32_e32 v155, 32, v143
	v_add_u32_e32 v156, 64, v156
	v_cmp_lt_i32_e32 vcc, v155, v156
	s_lshl_b32 s22, s68, 2
	s_or_b32 s22, s13, s22
	v_cndmask_b32_e32 v114, v143, v155, vcc
	s_lshl_b64 s[0:1], s[0:1], 8
	v_lshlrev_b32_e32 v114, 2, v114
	s_waitcnt lgkmcnt(0)
	v_add_f32_e32 v115, v115, v116
	s_add_u32 s0, s0, s6
	ds_bpermute_b32 v116, v114, v115
	s_addc_u32 s1, s1, s7
	s_ashr_i32 s23, s22, 31
	v_or_b32_e32 v146, s0, v145
	v_mov_b32_e32 v145, s1
	s_lshl_b64 s[0:1], s[22:23], 2
	v_and_b32_e32 v117, 48, v154
	s_add_u32 s0, s56, s0
	v_cmp_eq_u32_e64 s[6:7], 0, v117
	s_addc_u32 s1, s57, s1
	s_and_saveexec_b64 s[22:23], s[6:7]
	s_cbranch_execz .LBB0_397
	v_lshl_add_u64 v[118:119], s[20:21], 0, v[138:139]
	global_load_dword v118, v[118:119], off
	s_waitcnt lgkmcnt(0)
	v_add_f32_e32 v115, v115, v116
	v_mad_u64_u32 v[116:117], s[20:21], v146, 48, s[0:1]
	s_waitcnt vmcnt(0)
	v_add_f32_e32 v115, v115, v118
	v_fmamk_f32 v115, v115, 0x3c2aaaab, v144
	v_mul_f32_e32 v118, 0x4b800000, v115
	v_cmp_gt_f32_e32 vcc, s65, v115
	s_nop 1
	v_cndmask_b32_e32 v115, v115, v118, vcc
	v_rsq_f32_e32 v115, v115
	v_mov_b32_e32 v118, v117
	v_mad_u64_u32 v[118:119], s[20:21], v145, 48, v[118:119]
	v_mul_f32_e32 v117, 0x45800000, v115
	v_cndmask_b32_e32 v115, v115, v117, vcc
	v_mov_b32_e32 v117, v118
	global_store_dword v[116:117], v115, off

.LBB0_653:
	s_ashr_i32 s17, s16, 31
	s_lshl_b64 s[20:21], s[16:17], 17
	s_add_u32 s20, s48, s20
	s_addc_u32 s21, s49, s21
	s_and_b64 s[24:25], s[24:25], exec
	v_mov_b32_e32 v4, 0
	s_cselect_b32 s17, s21, s1
	s_cselect_b32 s23, s20, s0
	s_mov_b64 s[26:27], 0
	s_mov_b64 s[24:25], -1
	s_mov_b64 s[28:29], 0
	s_waitcnt lgkmcnt(0)
	v_mov_b32_e32 v5, v4
	v_mov_b32_e32 v6, v4
	v_mov_b32_e32 v7, v4
	v_mov_b32_e32 v8, v4
	v_mov_b32_e32 v9, v4
	v_mov_b32_e32 v10, v4
	v_mov_b32_e32 v11, v4
	v_mov_b32_e32 v20, v4
	v_mov_b32_e32 v21, v4
	v_mov_b32_e32 v22, v4
	v_mov_b32_e32 v23, v4
	v_mov_b32_e32 v24, v4
	v_mov_b32_e32 v25, v4
	v_mov_b32_e32 v26, v4
	v_mov_b32_e32 v27, v4
	v_mov_b32_e32 v36, v4
	v_mov_b32_e32 v37, v4
	v_mov_b32_e32 v38, v4
	v_mov_b32_e32 v39, v4
	v_mov_b32_e32 v40, v4
	v_mov_b32_e32 v41, v4
	v_mov_b32_e32 v42, v4
	v_mov_b32_e32 v43, v4
	v_mov_b32_e32 v52, v4
	v_mov_b32_e32 v53, v4
	v_mov_b32_e32 v54, v4
	v_mov_b32_e32 v55, v4
	v_mov_b32_e32 v56, v4
	v_mov_b32_e32 v57, v4
	v_mov_b32_e32 v58, v4
	v_mov_b32_e32 v59, v4
	v_mov_b32_e32 v12, v4
	v_mov_b32_e32 v13, v4
	v_mov_b32_e32 v14, v4
	v_mov_b32_e32 v15, v4
	v_mov_b32_e32 v16, v4
	v_mov_b32_e32 v17, v4
	v_mov_b32_e32 v18, v4
	v_mov_b32_e32 v19, v4
	v_mov_b32_e32 v28, v4
	v_mov_b32_e32 v29, v4
	v_mov_b32_e32 v30, v4
	v_mov_b32_e32 v31, v4
	v_mov_b32_e32 v32, v4
	v_mov_b32_e32 v33, v4
	v_mov_b32_e32 v34, v4
	v_mov_b32_e32 v35, v4
	v_mov_b32_e32 v44, v4
	v_mov_b32_e32 v45, v4
	v_mov_b32_e32 v46, v4
	v_mov_b32_e32 v47, v4
	v_mov_b32_e32 v48, v4
	v_mov_b32_e32 v49, v4
	v_mov_b32_e32 v50, v4
	v_mov_b32_e32 v51, v4
	v_mov_b32_e32 v60, v4
	v_mov_b32_e32 v61, v4
	v_mov_b32_e32 v62, v4
	v_mov_b32_e32 v63, v4
	v_mov_b32_e32 v64, v4
	v_mov_b32_e32 v65, v4
	v_mov_b32_e32 v66, v4
	v_mov_b32_e32 v67, v4
	v_mov_b32_e32 v68, v4
	v_mov_b32_e32 v69, v4
	v_mov_b32_e32 v70, v4
	v_mov_b32_e32 v71, v4
	v_mov_b32_e32 v72, v4
	v_mov_b32_e32 v73, v4
	v_mov_b32_e32 v74, v4
	v_mov_b32_e32 v75, v4
	v_mov_b32_e32 v84, v4
	v_mov_b32_e32 v85, v4
	v_mov_b32_e32 v86, v4
	v_mov_b32_e32 v87, v4
	v_mov_b32_e32 v88, v4
	v_mov_b32_e32 v89, v4
	v_mov_b32_e32 v90, v4
	v_mov_b32_e32 v91, v4
	v_mov_b32_e32 v100, v4
	v_mov_b32_e32 v101, v4
	v_mov_b32_e32 v102, v4
	v_mov_b32_e32 v103, v4
	v_mov_b32_e32 v104, v4
	v_mov_b32_e32 v105, v4
	v_mov_b32_e32 v106, v4
	v_mov_b32_e32 v107, v4
	v_mov_b32_e32 v116, v4
	v_mov_b32_e32 v117, v4
	v_mov_b32_e32 v118, v4
	v_mov_b32_e32 v119, v4
	v_mov_b32_e32 v120, v4
	v_mov_b32_e32 v121, v4
	v_mov_b32_e32 v122, v4
	v_mov_b32_e32 v123, v4
	v_mov_b32_e32 v76, v4
	v_mov_b32_e32 v77, v4
	v_mov_b32_e32 v78, v4
	v_mov_b32_e32 v79, v4
	v_mov_b32_e32 v80, v4
	v_mov_b32_e32 v81, v4
	v_mov_b32_e32 v82, v4
	v_mov_b32_e32 v83, v4
	v_mov_b32_e32 v92, v4
	v_mov_b32_e32 v93, v4
	v_mov_b32_e32 v94, v4
	v_mov_b32_e32 v95, v4
	v_mov_b32_e32 v96, v4
	v_mov_b32_e32 v97, v4
	v_mov_b32_e32 v98, v4
	v_mov_b32_e32 v99, v4
	v_mov_b32_e32 v108, v4
	v_mov_b32_e32 v109, v4
	v_mov_b32_e32 v110, v4
	v_mov_b32_e32 v111, v4
	v_mov_b32_e32 v112, v4
	v_mov_b32_e32 v113, v4
	v_mov_b32_e32 v114, v4
	v_mov_b32_e32 v115, v4
	v_mov_b32_e32 v124, v4
	v_mov_b32_e32 v125, v4
	v_mov_b32_e32 v126, v4
	v_mov_b32_e32 v127, v4
	v_mov_b32_e32 v128, v4
	v_mov_b32_e32 v129, v4
	v_mov_b32_e32 v130, v4
	v_mov_b32_e32 v131, v4
	s_waitcnt vmcnt(0)
.LBB0_654:
	s_add_u32 s36, s14, s26
	s_addc_u32 s37, s15, s27
	s_add_u32 s38, s36, 0x100
	s_addc_u32 s39, s37, 0
	s_and_b64 s[30:31], s[28:29], exec
	s_cselect_b32 s41, s19, s39
	s_cselect_b32 s40, s18, s38
	s_add_u32 s26, s0, s26
	s_addc_u32 s27, s1, s27
	s_add_u32 s30, s26, 0x100
	s_addc_u32 s31, s27, 0
	s_add_u32 s26, s40, 0x80
	s_addc_u32 s27, s41, 0
	s_add_i32 s81, 0, 0x10000
	s_and_b64 s[28:29], s[28:29], exec
	s_cselect_b32 s43, s17, s31
	s_cselect_b32 s42, s23, s30
	s_add_u32 s44, s36, 0x12080
	s_addc_u32 s45, s37, 0
	s_add_i32 s86, s81, s51
	s_add_i32 m0, s52, 0xc000
	s_add_i32 s87, s52, 0xe000
	s_add_i32 s85, 0, 0x14000
	s_add_i32 s84, s86, 0x2000
	s_add_u32 s38, s42, 0x10000
	s_addc_u32 s39, s43, 0
	s_add_i32 s82, s85, s51
	s_add_i32 s80, s82, 0x2000
	s_add_i32 s79, 0, 0x18000
	v_add_u32_e32 v152, s81, v1
	s_add_u32 s36, s40, 0x12000
	ds_read_b128 v[140:143], v152
	ds_read_b128 v[144:147], v152 offset:1024
	ds_read_b128 v[148:151], v152 offset:2048
	ds_read_b128 v[152:155], v152 offset:3072
	s_addc_u32 s37, s41, 0
	s_add_i32 s75, 0, 0x1c000
	s_add_u32 s30, s42, 0x80
	s_addc_u32 s31, s43, 0
	s_add_i32 s78, s79, s51
	s_add_i32 s74, s78, 0x2000
	s_add_u32 s28, s42, 0x10080
	s_addc_u32 s29, s43, 0
	s_add_i32 s83, s75, s51
	s_add_i32 s81, s83, 0x2000
	ds_read_b128 v[156:159], v3
	ds_read_b128 v[160:163], v3 offset:1024
	ds_read_b128 v[164:167], v3 offset:2048
	ds_read_b128 v[168:171], v3 offset:3072
	ds_read_b128 v[172:175], v3 offset:4096
	ds_read_b128 v[176:179], v3 offset:5120
	ds_read_b128 v[180:183], v3 offset:6144
	ds_read_b128 v[184:187], v3 offset:7168
	s_nop 0
	v_lshl_add_u64 v[188:189], s[44:45], 0, v[132:133]
	global_load_lds_dwordx4 v[188:189], off
	v_lshl_add_u64 v[188:189], s[44:45], 0, v[136:137]
	s_mov_b32 m0, s87
	s_nop 0
	global_load_lds_dwordx4 v[188:189], off
	s_waitcnt lgkmcnt(8)
	s_barrier
	s_waitcnt lgkmcnt(0)
	s_setprio 1
	s_waitcnt lgkmcnt(0)
	v_mfma_f32_16x16x32_bf16 v[128:131], v[140:143], v[156:159], v[128:131]
	v_mfma_f32_16x16x32_bf16 v[124:127], v[148:151], v[156:159], v[124:127]
	v_mfma_f32_16x16x32_bf16 v[112:115], v[140:143], v[164:167], v[112:115]
	v_mfma_f32_16x16x32_bf16 v[108:111], v[148:151], v[164:167], v[108:111]
	v_mfma_f32_16x16x32_bf16 v[96:99], v[140:143], v[172:175], v[96:99]
	v_mfma_f32_16x16x32_bf16 v[92:95], v[148:151], v[172:175], v[92:95]
	v_mfma_f32_16x16x32_bf16 v[80:83], v[140:143], v[180:183], v[80:83]
	v_mfma_f32_16x16x32_bf16 v[76:79], v[148:151], v[180:183], v[76:79]
	v_mfma_f32_16x16x32_bf16 v[128:131], v[144:147], v[160:163], v[128:131]
	v_mfma_f32_16x16x32_bf16 v[124:127], v[152:155], v[160:163], v[124:127]
	v_mfma_f32_16x16x32_bf16 v[112:115], v[144:147], v[168:171], v[112:115]
	v_mfma_f32_16x16x32_bf16 v[108:111], v[152:155], v[168:171], v[108:111]
	v_mfma_f32_16x16x32_bf16 v[96:99], v[144:147], v[176:179], v[96:99]
	v_mfma_f32_16x16x32_bf16 v[92:95], v[152:155], v[176:179], v[92:95]
	v_mfma_f32_16x16x32_bf16 v[80:83], v[144:147], v[184:187], v[80:83]
	v_mfma_f32_16x16x32_bf16 v[76:79], v[152:155], v[184:187], v[76:79]
	s_setprio 0
	s_barrier
	v_add_u32_e32 v214, s85, v1
	s_mov_b32 m0, s86
	ds_read_b128 v[188:191], v214
	ds_read_b128 v[192:195], v214 offset:1024
	ds_read_b128 v[210:213], v214 offset:2048
	ds_read_b128 v[214:217], v214 offset:3072
	s_nop 0
	v_lshl_add_u64 v[218:219], s[42:43], 0, v[134:135]
	global_load_lds_dwordx4 v[218:219], off
	v_lshl_add_u64 v[218:219], s[42:43], 0, v[138:139]
	s_mov_b32 m0, s84
	s_nop 0
	global_load_lds_dwordx4 v[218:219], off
	s_barrier
	s_waitcnt lgkmcnt(0)
	s_setprio 1
	s_waitcnt lgkmcnt(0)
	v_mfma_f32_16x16x32_bf16 v[120:123], v[188:191], v[156:159], v[120:123]
	v_mfma_f32_16x16x32_bf16 v[116:119], v[210:213], v[156:159], v[116:119]
	v_mfma_f32_16x16x32_bf16 v[104:107], v[188:191], v[164:167], v[104:107]
	v_mfma_f32_16x16x32_bf16 v[100:103], v[210:213], v[164:167], v[100:103]
	v_mfma_f32_16x16x32_bf16 v[88:91], v[188:191], v[172:175], v[88:91]
	v_mfma_f32_16x16x32_bf16 v[84:87], v[210:213], v[172:175], v[84:87]
	v_mfma_f32_16x16x32_bf16 v[72:75], v[188:191], v[180:183], v[72:75]
	v_mfma_f32_16x16x32_bf16 v[68:71], v[210:213], v[180:183], v[68:71]
	v_mfma_f32_16x16x32_bf16 v[120:123], v[192:195], v[160:163], v[120:123]
	v_mfma_f32_16x16x32_bf16 v[116:119], v[214:217], v[160:163], v[116:119]
	v_mfma_f32_16x16x32_bf16 v[104:107], v[192:195], v[168:171], v[104:107]
	v_mfma_f32_16x16x32_bf16 v[100:103], v[214:217], v[168:171], v[100:103]
	v_mfma_f32_16x16x32_bf16 v[88:91], v[192:195], v[176:179], v[88:91]
	v_mfma_f32_16x16x32_bf16 v[84:87], v[214:217], v[176:179], v[84:87]
	v_mfma_f32_16x16x32_bf16 v[72:75], v[192:195], v[184:187], v[72:75]
	v_mfma_f32_16x16x32_bf16 v[68:71], v[214:217], v[184:187], v[68:71]
	s_setprio 0
	s_mov_b32 m0, s52
	s_barrier
	ds_read_b128 v[156:159], v3 offset:16384
	ds_read_b128 v[160:163], v3 offset:17408
	ds_read_b128 v[164:167], v3 offset:18432
	ds_read_b128 v[168:171], v3 offset:19456
	ds_read_b128 v[172:175], v3 offset:20480
	ds_read_b128 v[176:179], v3 offset:21504
	ds_read_b128 v[180:183], v3 offset:22528
	ds_read_b128 v[184:187], v3 offset:23552
	s_nop 0
	v_lshl_add_u64 v[218:219], s[40:41], 0, v[132:133]
	global_load_lds_dwordx4 v[218:219], off
	v_lshl_add_u64 v[218:219], s[40:41], 0, v[136:137]
	s_mov_b32 m0, s53
	s_nop 0
	global_load_lds_dwordx4 v[218:219], off
	s_barrier
	s_waitcnt lgkmcnt(0)
	s_setprio 1
	s_waitcnt lgkmcnt(0)
	v_mfma_f32_16x16x32_bf16 v[64:67], v[140:143], v[156:159], v[64:67]
	v_mfma_f32_16x16x32_bf16 v[60:63], v[148:151], v[156:159], v[60:63]
	v_mfma_f32_16x16x32_bf16 v[48:51], v[140:143], v[164:167], v[48:51]
	v_mfma_f32_16x16x32_bf16 v[44:47], v[148:151], v[164:167], v[44:47]
	v_mfma_f32_16x16x32_bf16 v[32:35], v[140:143], v[172:175], v[32:35]
	v_mfma_f32_16x16x32_bf16 v[28:31], v[148:151], v[172:175], v[28:31]
	v_mfma_f32_16x16x32_bf16 v[16:19], v[140:143], v[180:183], v[16:19]
	v_mfma_f32_16x16x32_bf16 v[12:15], v[148:151], v[180:183], v[12:15]
	v_mfma_f32_16x16x32_bf16 v[64:67], v[144:147], v[160:163], v[64:67]
	v_mfma_f32_16x16x32_bf16 v[60:63], v[152:155], v[160:163], v[60:63]
	v_mfma_f32_16x16x32_bf16 v[48:51], v[144:147], v[168:171], v[48:51]
	v_mfma_f32_16x16x32_bf16 v[44:47], v[152:155], v[168:171], v[44:47]
	v_mfma_f32_16x16x32_bf16 v[32:35], v[144:147], v[176:179], v[32:35]
	v_mfma_f32_16x16x32_bf16 v[28:31], v[152:155], v[176:179], v[28:31]
	v_mfma_f32_16x16x32_bf16 v[16:19], v[144:147], v[184:187], v[16:19]
	v_mfma_f32_16x16x32_bf16 v[12:15], v[152:155], v[184:187], v[12:15]
	s_setprio 0
	s_barrier
	s_mov_b32 m0, s82
	s_nop 0
	v_lshl_add_u64 v[140:141], s[38:39], 0, v[134:135]
	global_load_lds_dwordx4 v[140:141], off
	v_lshl_add_u64 v[140:141], s[38:39], 0, v[138:139]
	s_mov_b32 m0, s80
	s_nop 0
	global_load_lds_dwordx4 v[140:141], off
	s_waitcnt vmcnt(6)
	s_barrier
	s_setprio 1
	v_mfma_f32_16x16x32_bf16 v[56:59], v[188:191], v[156:159], v[56:59]
	v_mfma_f32_16x16x32_bf16 v[52:55], v[210:213], v[156:159], v[52:55]
	v_mfma_f32_16x16x32_bf16 v[40:43], v[188:191], v[164:167], v[40:43]
	v_mfma_f32_16x16x32_bf16 v[36:39], v[210:213], v[164:167], v[36:39]
	v_mfma_f32_16x16x32_bf16 v[24:27], v[188:191], v[172:175], v[24:27]
	v_mfma_f32_16x16x32_bf16 v[20:23], v[210:213], v[172:175], v[20:23]
	v_mfma_f32_16x16x32_bf16 v[8:11], v[188:191], v[180:183], v[8:11]
	v_mfma_f32_16x16x32_bf16 v[4:7], v[210:213], v[180:183], v[4:7]
	v_mfma_f32_16x16x32_bf16 v[56:59], v[192:195], v[160:163], v[56:59]
	v_mfma_f32_16x16x32_bf16 v[52:55], v[214:217], v[160:163], v[52:55]
	v_mfma_f32_16x16x32_bf16 v[40:43], v[192:195], v[168:171], v[40:43]
	v_mfma_f32_16x16x32_bf16 v[36:39], v[214:217], v[168:171], v[36:39]
	v_mfma_f32_16x16x32_bf16 v[24:27], v[192:195], v[176:179], v[24:27]
	v_mfma_f32_16x16x32_bf16 v[20:23], v[214:217], v[176:179], v[20:23]
	v_mfma_f32_16x16x32_bf16 v[8:11], v[192:195], v[184:187], v[8:11]
	v_mfma_f32_16x16x32_bf16 v[4:7], v[214:217], v[184:187], v[4:7]
	s_setprio 0
	v_add_u32_e32 v152, s79, v1
	s_barrier
	ds_read_b128 v[140:143], v152
	ds_read_b128 v[144:147], v152 offset:1024
	ds_read_b128 v[148:151], v152 offset:2048
	ds_read_b128 v[152:155], v152 offset:3072
	s_mov_b32 m0, s55
	ds_read_b128 v[156:159], v3 offset:32768
	ds_read_b128 v[160:163], v3 offset:33792
	ds_read_b128 v[164:167], v3 offset:34816
	ds_read_b128 v[168:171], v3 offset:35840
	ds_read_b128 v[172:175], v3 offset:36864
	ds_read_b128 v[176:179], v3 offset:37888
	ds_read_b128 v[180:183], v3 offset:38912
	ds_read_b128 v[184:187], v3 offset:39936
	s_nop 0
	v_lshl_add_u64 v[188:189], s[36:37], 0, v[132:133]
	global_load_lds_dwordx4 v[188:189], off
	v_lshl_add_u64 v[188:189], s[36:37], 0, v[136:137]
	s_mov_b32 m0, s56
	s_nop 0
	global_load_lds_dwordx4 v[188:189], off
	s_waitcnt lgkmcnt(8)
	s_barrier
	s_waitcnt lgkmcnt(0)
	s_setprio 1
	s_waitcnt lgkmcnt(0)
	v_mfma_f32_16x16x32_bf16 v[128:131], v[140:143], v[156:159], v[128:131]
	v_mfma_f32_16x16x32_bf16 v[124:127], v[148:151], v[156:159], v[124:127]
	v_mfma_f32_16x16x32_bf16 v[112:115], v[140:143], v[164:167], v[112:115]
	v_mfma_f32_16x16x32_bf16 v[108:111], v[148:151], v[164:167], v[108:111]
	v_mfma_f32_16x16x32_bf16 v[96:99], v[140:143], v[172:175], v[96:99]
	v_mfma_f32_16x16x32_bf16 v[92:95], v[148:151], v[172:175], v[92:95]
	v_mfma_f32_16x16x32_bf16 v[80:83], v[140:143], v[180:183], v[80:83]
	v_mfma_f32_16x16x32_bf16 v[76:79], v[148:151], v[180:183], v[76:79]
	v_mfma_f32_16x16x32_bf16 v[128:131], v[144:147], v[160:163], v[128:131]
	v_mfma_f32_16x16x32_bf16 v[124:127], v[152:155], v[160:163], v[124:127]
	v_mfma_f32_16x16x32_bf16 v[112:115], v[144:147], v[168:171], v[112:115]
	v_mfma_f32_16x16x32_bf16 v[108:111], v[152:155], v[168:171], v[108:111]
	v_mfma_f32_16x16x32_bf16 v[96:99], v[144:147], v[176:179], v[96:99]
	v_mfma_f32_16x16x32_bf16 v[92:95], v[152:155], v[176:179], v[92:95]
	v_mfma_f32_16x16x32_bf16 v[80:83], v[144:147], v[184:187], v[80:83]
	v_mfma_f32_16x16x32_bf16 v[76:79], v[152:155], v[184:187], v[76:79]
	s_setprio 0
	s_barrier
	v_add_u32_e32 v214, s75, v1
	s_mov_b32 m0, s78
	ds_read_b128 v[188:191], v214
	ds_read_b128 v[192:195], v214 offset:1024
	ds_read_b128 v[210:213], v214 offset:2048
	ds_read_b128 v[214:217], v214 offset:3072
	s_nop 0
	v_lshl_add_u64 v[218:219], s[30:31], 0, v[134:135]
	global_load_lds_dwordx4 v[218:219], off
	v_lshl_add_u64 v[218:219], s[30:31], 0, v[138:139]
	s_mov_b32 m0, s74
	s_nop 0
	global_load_lds_dwordx4 v[218:219], off
	s_barrier
	s_waitcnt lgkmcnt(0)
	s_setprio 1
	s_waitcnt lgkmcnt(0)
	v_mfma_f32_16x16x32_bf16 v[120:123], v[188:191], v[156:159], v[120:123]
	v_mfma_f32_16x16x32_bf16 v[116:119], v[210:213], v[156:159], v[116:119]
	v_mfma_f32_16x16x32_bf16 v[104:107], v[188:191], v[164:167], v[104:107]
	v_mfma_f32_16x16x32_bf16 v[100:103], v[210:213], v[164:167], v[100:103]
	v_mfma_f32_16x16x32_bf16 v[88:91], v[188:191], v[172:175], v[88:91]
	v_mfma_f32_16x16x32_bf16 v[84:87], v[210:213], v[172:175], v[84:87]
	v_mfma_f32_16x16x32_bf16 v[72:75], v[188:191], v[180:183], v[72:75]
	v_mfma_f32_16x16x32_bf16 v[68:71], v[210:213], v[180:183], v[68:71]
	v_mfma_f32_16x16x32_bf16 v[120:123], v[192:195], v[160:163], v[120:123]
	v_mfma_f32_16x16x32_bf16 v[116:119], v[214:217], v[160:163], v[116:119]
	v_mfma_f32_16x16x32_bf16 v[104:107], v[192:195], v[168:171], v[104:107]
	v_mfma_f32_16x16x32_bf16 v[100:103], v[214:217], v[168:171], v[100:103]
	v_mfma_f32_16x16x32_bf16 v[88:91], v[192:195], v[176:179], v[88:91]
	v_mfma_f32_16x16x32_bf16 v[84:87], v[214:217], v[176:179], v[84:87]
	v_mfma_f32_16x16x32_bf16 v[72:75], v[192:195], v[184:187], v[72:75]
	v_mfma_f32_16x16x32_bf16 v[68:71], v[214:217], v[184:187], v[68:71]
	s_setprio 0
	s_mov_b32 m0, s65
	s_barrier
	ds_read_b128 v[156:159], v3 offset:49152
	ds_read_b128 v[160:163], v3 offset:50176
	ds_read_b128 v[164:167], v3 offset:51200
	ds_read_b128 v[168:171], v3 offset:52224
	ds_read_b128 v[172:175], v3 offset:53248
	ds_read_b128 v[176:179], v3 offset:54272
	ds_read_b128 v[180:183], v3 offset:55296
	ds_read_b128 v[184:187], v3 offset:56320
	s_nop 0
	v_lshl_add_u64 v[218:219], s[26:27], 0, v[132:133]
	global_load_lds_dwordx4 v[218:219], off
	v_lshl_add_u64 v[218:219], s[26:27], 0, v[136:137]
	s_mov_b32 m0, s67
	s_nop 0
	global_load_lds_dwordx4 v[218:219], off
	s_barrier
	s_waitcnt lgkmcnt(0)
	s_setprio 1
	s_waitcnt lgkmcnt(0)
	v_mfma_f32_16x16x32_bf16 v[64:67], v[140:143], v[156:159], v[64:67]
	v_mfma_f32_16x16x32_bf16 v[60:63], v[148:151], v[156:159], v[60:63]
	v_mfma_f32_16x16x32_bf16 v[48:51], v[140:143], v[164:167], v[48:51]
	v_mfma_f32_16x16x32_bf16 v[44:47], v[148:151], v[164:167], v[44:47]
	v_mfma_f32_16x16x32_bf16 v[32:35], v[140:143], v[172:175], v[32:35]
	v_mfma_f32_16x16x32_bf16 v[28:31], v[148:151], v[172:175], v[28:31]
	v_mfma_f32_16x16x32_bf16 v[16:19], v[140:143], v[180:183], v[16:19]
	v_mfma_f32_16x16x32_bf16 v[12:15], v[148:151], v[180:183], v[12:15]
	v_mfma_f32_16x16x32_bf16 v[64:67], v[144:147], v[160:163], v[64:67]
	v_mfma_f32_16x16x32_bf16 v[60:63], v[152:155], v[160:163], v[60:63]
	v_mfma_f32_16x16x32_bf16 v[48:51], v[144:147], v[168:171], v[48:51]
	v_mfma_f32_16x16x32_bf16 v[44:47], v[152:155], v[168:171], v[44:47]
	v_mfma_f32_16x16x32_bf16 v[32:35], v[144:147], v[176:179], v[32:35]
	v_mfma_f32_16x16x32_bf16 v[28:31], v[152:155], v[176:179], v[28:31]
	v_mfma_f32_16x16x32_bf16 v[16:19], v[144:147], v[184:187], v[16:19]
	v_mfma_f32_16x16x32_bf16 v[12:15], v[152:155], v[184:187], v[12:15]
	s_setprio 0
	s_barrier
	s_mov_b32 m0, s83
	s_nop 0
	v_lshl_add_u64 v[140:141], s[28:29], 0, v[134:135]
	global_load_lds_dwordx4 v[140:141], off
	v_lshl_add_u64 v[140:141], s[28:29], 0, v[138:139]
	s_mov_b32 m0, s81
	s_nop 0
	global_load_lds_dwordx4 v[140:141], off
	s_waitcnt vmcnt(6)
	s_barrier
	s_setprio 1
	v_mfma_f32_16x16x32_bf16 v[56:59], v[188:191], v[156:159], v[56:59]
	v_mfma_f32_16x16x32_bf16 v[52:55], v[210:213], v[156:159], v[52:55]
	v_mfma_f32_16x16x32_bf16 v[40:43], v[188:191], v[164:167], v[40:43]
	v_mfma_f32_16x16x32_bf16 v[36:39], v[210:213], v[164:167], v[36:39]
	v_mfma_f32_16x16x32_bf16 v[24:27], v[188:191], v[172:175], v[24:27]
	v_mfma_f32_16x16x32_bf16 v[20:23], v[210:213], v[172:175], v[20:23]
	v_mfma_f32_16x16x32_bf16 v[8:11], v[188:191], v[180:183], v[8:11]
	v_mfma_f32_16x16x32_bf16 v[4:7], v[210:213], v[180:183], v[4:7]
	v_mfma_f32_16x16x32_bf16 v[56:59], v[192:195], v[160:163], v[56:59]
	v_mfma_f32_16x16x32_bf16 v[52:55], v[214:217], v[160:163], v[52:55]
	v_mfma_f32_16x16x32_bf16 v[40:43], v[192:195], v[168:171], v[40:43]
	v_mfma_f32_16x16x32_bf16 v[36:39], v[214:217], v[168:171], v[36:39]
	v_mfma_f32_16x16x32_bf16 v[24:27], v[192:195], v[176:179], v[24:27]
	v_mfma_f32_16x16x32_bf16 v[20:23], v[214:217], v[176:179], v[20:23]
	v_mfma_f32_16x16x32_bf16 v[8:11], v[192:195], v[184:187], v[8:11]
	v_mfma_f32_16x16x32_bf16 v[4:7], v[214:217], v[184:187], v[4:7]
	s_setprio 0
	s_andn2_b64 vcc, exec, s[24:25]
	s_mov_b64 s[28:29], -1
	s_mov_b64 s[24:25], 0
	s_mov_b64 s[26:27], 0x100
	s_barrier
	s_cbranch_vccz .LBB0_654
	v_mov_b32_e32 v141, v0
	s_ashr_i32 s23, s22, 31
	v_readfirstlane_b32 s0, v141
	s_bfe_u32 s17, s0, 0x20006
	s_ashr_i32 s0, s0, 2
	s_andn2_b32 s0, s0, 63
	s_ashr_i32 s1, s0, 31
	s_lshl_b64 s[14:15], s[22:23], 10
	s_add_u32 s24, s57, s14
	s_addc_u32 s25, s62, s15
	s_lshl_b64 s[14:15], s[0:1], 2
	v_and_b32_e32 v142, 15, v141
	s_add_u32 s24, s24, s14
	s_addc_u32 s25, s25, s15
	v_lshlrev_b32_e32 v140, 2, v142
	global_load_dword v150, v140, s[24:25] offset:64
	global_load_dword v149, v140, s[24:25] offset:128
	global_load_dword v148, v140, s[24:25] offset:192
	global_load_dword v147, v140, s[24:25] offset:512
	global_load_dword v146, v140, s[24:25] offset:576
	global_load_dword v145, v140, s[24:25] offset:640
	global_load_dword v144, v140, s[24:25] offset:704
	v_mul_f32_e32 v129, v129, v129
	v_mul_f32_e32 v125, v125, v125
	v_mul_f32_e32 v121, v121, v121
	v_mul_f32_e32 v117, v117, v117
	v_fmac_f32_e32 v129, v128, v128
	v_mul_f32_e32 v128, v131, v131
	v_fmac_f32_e32 v125, v124, v124
	v_mul_f32_e32 v124, v127, v127
	v_fmac_f32_e32 v121, v120, v120
	v_mul_f32_e32 v120, v123, v123
	v_fmac_f32_e32 v117, v116, v116
	v_mul_f32_e32 v116, v119, v119
	v_fmac_f32_e32 v128, v130, v130
	v_fmac_f32_e32 v124, v126, v126
	v_fmac_f32_e32 v120, v122, v122
	v_fmac_f32_e32 v116, v118, v118
	v_add_f32_e32 v128, v129, v128
	v_add_f32_e32 v124, v125, v124
	v_add_f32_e32 v120, v121, v120
	v_add_f32_e32 v116, v117, v116
	v_add_f32_e32 v124, v128, v124
	v_add_f32_e32 v116, v120, v116
	v_add_f32_e32 v117, v124, v116
	ds_swizzle_b32 v118, v117 offset:swizzle(SWAP,16)
	v_and_b32_e32 v152, 64, v236
	v_xor_b32_e32 v151, 32, v236
	v_add_u32_e32 v152, 64, v152
	v_cmp_lt_i32_e32 vcc, v151, v152
	s_lshl_b32 s14, s73, 2
	s_or_b32 s26, s17, s14
	v_cndmask_b32_e32 v116, v236, v151, vcc
	s_lshl_b64 s[14:15], s[22:23], 8
	v_lshlrev_b32_e32 v116, 2, v116
	s_waitcnt lgkmcnt(0)
	v_add_f32_e32 v117, v117, v118
	s_add_u32 s0, s14, s0
	ds_bpermute_b32 v118, v116, v117
	s_addc_u32 s1, s15, s1
	s_ashr_i32 s27, s26, 31
	v_or_b32_e32 v143, s0, v142
	v_mov_b32_e32 v142, s1
	s_lshl_b64 s[0:1], s[26:27], 2
	v_and_b32_e32 v119, 48, v141
	s_add_u32 s0, s63, s0
	v_cmp_eq_u32_e64 s[14:15], 0, v119
	s_addc_u32 s1, s64, s1
	s_and_saveexec_b64 s[22:23], s[14:15]
	s_cbranch_execz .LBB0_657
	v_mov_b32_e32 v141, v2
	v_lshl_add_u64 v[120:121], s[24:25], 0, v[140:141]
	global_load_dword v119, v[120:121], off
	s_waitcnt lgkmcnt(0)
	v_add_f32_e32 v117, v117, v118
	s_waitcnt vmcnt(0)
	v_add_f32_e32 v117, v117, v119
	v_fmamk_f32 v117, v117, 0x3c2aaaab, v231
	v_cmp_gt_f32_e32 vcc, s11, v117
	v_mul_f32_e32 v118, 0x4b800000, v117
	s_nop 0
	v_cndmask_b32_e32 v117, v117, v118, vcc
	v_rsq_f32_e32 v117, v117
	s_nop 0
	v_mul_f32_e32 v118, 0x45800000, v117
	v_cndmask_b32_e32 v117, v117, v118, vcc
	v_mad_u64_u32 v[118:119], s[24:25], v143, 48, s[0:1]
	v_mov_b32_e32 v120, v119
	v_mad_u64_u32 v[120:121], s[24:25], v142, 48, v[120:121]
	v_mov_b32_e32 v119, v120
	global_store_dword v[118:119], v117, off

.LBB0_1011:
	s_ashr_i32 s29, s28, 31
	s_lshl_b64 s[34:35], s[28:29], 17
	s_add_u32 s34, s53, s34
	s_addc_u32 s35, s54, s35
	s_and_b64 s[16:17], s[16:17], exec
	v_mov_b32_e32 v4, 0
	s_cselect_b32 s9, s35, s1
	s_cselect_b32 s19, s34, s0
	s_mov_b64 s[36:37], 0
	s_mov_b64 s[16:17], -1
	s_mov_b64 s[38:39], 0
	v_mov_b32_e32 v5, v4
	v_mov_b32_e32 v6, v4
	v_mov_b32_e32 v7, v4
	v_mov_b32_e32 v8, v4
	v_mov_b32_e32 v9, v4
	v_mov_b32_e32 v10, v4
	v_mov_b32_e32 v11, v4
	v_mov_b32_e32 v20, v4
	v_mov_b32_e32 v21, v4
	v_mov_b32_e32 v22, v4
	v_mov_b32_e32 v23, v4
	v_mov_b32_e32 v24, v4
	v_mov_b32_e32 v25, v4
	v_mov_b32_e32 v26, v4
	v_mov_b32_e32 v27, v4
	v_mov_b32_e32 v36, v4
	v_mov_b32_e32 v37, v4
	v_mov_b32_e32 v38, v4
	v_mov_b32_e32 v39, v4
	v_mov_b32_e32 v40, v4
	v_mov_b32_e32 v41, v4
	v_mov_b32_e32 v42, v4
	v_mov_b32_e32 v43, v4
	v_mov_b32_e32 v52, v4
	v_mov_b32_e32 v53, v4
	v_mov_b32_e32 v54, v4
	v_mov_b32_e32 v55, v4
	v_mov_b32_e32 v56, v4
	v_mov_b32_e32 v57, v4
	v_mov_b32_e32 v58, v4
	v_mov_b32_e32 v59, v4
	v_mov_b32_e32 v12, v4
	v_mov_b32_e32 v13, v4
	v_mov_b32_e32 v14, v4
	v_mov_b32_e32 v15, v4
	v_mov_b32_e32 v16, v4
	v_mov_b32_e32 v17, v4
	v_mov_b32_e32 v18, v4
	v_mov_b32_e32 v19, v4
	v_mov_b32_e32 v28, v4
	v_mov_b32_e32 v29, v4
	v_mov_b32_e32 v30, v4
	v_mov_b32_e32 v31, v4
	v_mov_b32_e32 v32, v4
	v_mov_b32_e32 v33, v4
	v_mov_b32_e32 v34, v4
	v_mov_b32_e32 v35, v4
	v_mov_b32_e32 v44, v4
	v_mov_b32_e32 v45, v4
	v_mov_b32_e32 v46, v4
	v_mov_b32_e32 v47, v4
	v_mov_b32_e32 v48, v4
	v_mov_b32_e32 v49, v4
	v_mov_b32_e32 v50, v4
	v_mov_b32_e32 v51, v4
	v_mov_b32_e32 v60, v4
	v_mov_b32_e32 v61, v4
	v_mov_b32_e32 v62, v4
	v_mov_b32_e32 v63, v4
	v_mov_b32_e32 v64, v4
	v_mov_b32_e32 v65, v4
	v_mov_b32_e32 v66, v4
	v_mov_b32_e32 v67, v4
	v_mov_b32_e32 v72, v4
	v_mov_b32_e32 v73, v4
	v_mov_b32_e32 v74, v4
	v_mov_b32_e32 v75, v4
	v_mov_b32_e32 v76, v4
	v_mov_b32_e32 v77, v4
	v_mov_b32_e32 v78, v4
	v_mov_b32_e32 v79, v4
	v_mov_b32_e32 v92, v4
	v_mov_b32_e32 v93, v4
	v_mov_b32_e32 v94, v4
	v_mov_b32_e32 v95, v4
	v_mov_b32_e32 v96, v4
	v_mov_b32_e32 v97, v4
	v_mov_b32_e32 v98, v4
	v_mov_b32_e32 v99, v4
	v_mov_b32_e32 v112, v4
	v_mov_b32_e32 v113, v4
	v_mov_b32_e32 v114, v4
	v_mov_b32_e32 v115, v4
	v_mov_b32_e32 v116, v4
	v_mov_b32_e32 v117, v4
	v_mov_b32_e32 v118, v4
	v_mov_b32_e32 v119, v4
	v_mov_b32_e32 v132, v4
	v_mov_b32_e32 v133, v4
	v_mov_b32_e32 v134, v4
	v_mov_b32_e32 v135, v4
	v_mov_b32_e32 v136, v4
	v_mov_b32_e32 v137, v4
	v_mov_b32_e32 v138, v4
	v_mov_b32_e32 v139, v4
	v_mov_b32_e32 v80, v4
	v_mov_b32_e32 v81, v4
	v_mov_b32_e32 v82, v4
	v_mov_b32_e32 v83, v4
	v_mov_b32_e32 v84, v4
	v_mov_b32_e32 v85, v4
	v_mov_b32_e32 v86, v4
	v_mov_b32_e32 v87, v4
	v_mov_b32_e32 v100, v4
	v_mov_b32_e32 v101, v4
	v_mov_b32_e32 v102, v4
	v_mov_b32_e32 v103, v4
	v_mov_b32_e32 v104, v4
	v_mov_b32_e32 v105, v4
	v_mov_b32_e32 v106, v4
	v_mov_b32_e32 v107, v4
	v_mov_b32_e32 v120, v4
	v_mov_b32_e32 v121, v4
	v_mov_b32_e32 v122, v4
	v_mov_b32_e32 v123, v4
	v_mov_b32_e32 v124, v4
	v_mov_b32_e32 v125, v4
	v_mov_b32_e32 v126, v4
	v_mov_b32_e32 v127, v4
	v_mov_b32_e32 v140, v4
	v_mov_b32_e32 v141, v4
	v_mov_b32_e32 v142, v4
	v_mov_b32_e32 v143, v4
	v_mov_b32_e32 v144, v4
	v_mov_b32_e32 v145, v4
	v_mov_b32_e32 v146, v4
	v_mov_b32_e32 v147, v4
	s_waitcnt vmcnt(0)
.LBB0_1012:
	s_add_u32 s29, s20, s36
	s_addc_u32 s42, s21, s37
	s_add_u32 s43, s29, 0x100
	s_addc_u32 s44, s42, 0
	s_and_b64 s[40:41], s[38:39], exec
	s_cselect_b32 s47, s31, s44
	s_cselect_b32 s46, s30, s43
	s_add_u32 s36, s0, s36
	s_addc_u32 s37, s1, s37
	s_add_u32 s40, s36, 0x100
	s_addc_u32 s41, s37, 0
	s_add_u32 s36, s46, 0x80
	s_addc_u32 s37, s47, 0
	s_add_i32 s78, 0, 0x10000
	s_and_b64 s[38:39], s[38:39], exec
	s_cselect_b32 s49, s9, s41
	s_cselect_b32 s48, s19, s40
	s_add_u32 s50, s29, 0x12080
	s_addc_u32 s51, s42, 0
	s_add_i32 s83, s78, s55
	s_add_i32 m0, s56, 0xc000
	s_add_i32 s84, s56, 0xe000
	s_add_i32 s82, 0, 0x14000
	s_add_i32 s81, s83, 0x2000
	s_add_u32 s44, s48, 0x10000
	s_addc_u32 s45, s49, 0
	s_add_i32 s79, s82, s55
	s_add_i32 s75, s79, 0x2000
	s_add_i32 s74, 0, 0x18000
	v_add_u32_e32 v128, s78, v1
	s_add_u32 s42, s46, 0x12000
	ds_read_b128 v[68:71], v128
	ds_read_b128 v[88:91], v128 offset:1024
	ds_read_b128 v[108:111], v128 offset:2048
	ds_read_b128 v[128:131], v128 offset:3072
	s_addc_u32 s43, s47, 0
	s_add_i32 s67, 0, 0x1c000
	s_add_u32 s40, s48, 0x80
	s_addc_u32 s41, s49, 0
	s_add_i32 s68, s74, s55
	s_add_i32 s29, s68, 0x2000
	s_add_u32 s38, s48, 0x10080
	s_addc_u32 s39, s49, 0
	s_add_i32 s80, s67, s55
	s_add_i32 s78, s80, 0x2000
	ds_read_b128 v[148:151], v3
	ds_read_b128 v[152:155], v3 offset:1024
	ds_read_b128 v[156:159], v3 offset:2048
	ds_read_b128 v[160:163], v3 offset:3072
	ds_read_b128 v[172:175], v3 offset:4096
	ds_read_b128 v[176:179], v3 offset:5120
	ds_read_b128 v[180:183], v3 offset:6144
	ds_read_b128 v[184:187], v3 offset:7168
	s_nop 0
	v_lshl_add_u64 v[188:189], s[50:51], 0, v[164:165]
	global_load_lds_dwordx4 v[188:189], off
	v_lshl_add_u64 v[188:189], s[50:51], 0, v[168:169]
	s_mov_b32 m0, s84
	s_nop 0
	global_load_lds_dwordx4 v[188:189], off
	s_waitcnt lgkmcnt(8)
	s_barrier
	s_waitcnt lgkmcnt(0)
	s_setprio 1
	s_waitcnt lgkmcnt(0)
	v_mfma_f32_16x16x32_bf16 v[144:147], v[68:71], v[148:151], v[144:147]
	v_mfma_f32_16x16x32_bf16 v[140:143], v[108:111], v[148:151], v[140:143]
	v_mfma_f32_16x16x32_bf16 v[124:127], v[68:71], v[156:159], v[124:127]
	v_mfma_f32_16x16x32_bf16 v[120:123], v[108:111], v[156:159], v[120:123]
	v_mfma_f32_16x16x32_bf16 v[104:107], v[68:71], v[172:175], v[104:107]
	v_mfma_f32_16x16x32_bf16 v[100:103], v[108:111], v[172:175], v[100:103]
	v_mfma_f32_16x16x32_bf16 v[84:87], v[68:71], v[180:183], v[84:87]
	v_mfma_f32_16x16x32_bf16 v[80:83], v[108:111], v[180:183], v[80:83]
	v_mfma_f32_16x16x32_bf16 v[144:147], v[88:91], v[152:155], v[144:147]
	v_mfma_f32_16x16x32_bf16 v[140:143], v[128:131], v[152:155], v[140:143]
	v_mfma_f32_16x16x32_bf16 v[124:127], v[88:91], v[160:163], v[124:127]
	v_mfma_f32_16x16x32_bf16 v[120:123], v[128:131], v[160:163], v[120:123]
	v_mfma_f32_16x16x32_bf16 v[104:107], v[88:91], v[176:179], v[104:107]
	v_mfma_f32_16x16x32_bf16 v[100:103], v[128:131], v[176:179], v[100:103]
	v_mfma_f32_16x16x32_bf16 v[84:87], v[88:91], v[184:187], v[84:87]
	v_mfma_f32_16x16x32_bf16 v[80:83], v[128:131], v[184:187], v[80:83]
	s_setprio 0
	s_barrier
	v_add_u32_e32 v214, s82, v1
	s_mov_b32 m0, s83
	ds_read_b128 v[188:191], v214
	ds_read_b128 v[192:195], v214 offset:1024
	ds_read_b128 v[210:213], v214 offset:2048
	ds_read_b128 v[214:217], v214 offset:3072
	s_nop 0
	v_lshl_add_u64 v[218:219], s[48:49], 0, v[166:167]
	global_load_lds_dwordx4 v[218:219], off
	v_lshl_add_u64 v[218:219], s[48:49], 0, v[170:171]
	s_mov_b32 m0, s81
	s_nop 0
	global_load_lds_dwordx4 v[218:219], off
	s_barrier
	s_waitcnt lgkmcnt(0)
	s_setprio 1
	s_waitcnt lgkmcnt(0)
	v_mfma_f32_16x16x32_bf16 v[136:139], v[188:191], v[148:151], v[136:139]
	v_mfma_f32_16x16x32_bf16 v[132:135], v[210:213], v[148:151], v[132:135]
	v_mfma_f32_16x16x32_bf16 v[116:119], v[188:191], v[156:159], v[116:119]
	v_mfma_f32_16x16x32_bf16 v[112:115], v[210:213], v[156:159], v[112:115]
	v_mfma_f32_16x16x32_bf16 v[96:99], v[188:191], v[172:175], v[96:99]
	v_mfma_f32_16x16x32_bf16 v[92:95], v[210:213], v[172:175], v[92:95]
	v_mfma_f32_16x16x32_bf16 v[76:79], v[188:191], v[180:183], v[76:79]
	v_mfma_f32_16x16x32_bf16 v[72:75], v[210:213], v[180:183], v[72:75]
	v_mfma_f32_16x16x32_bf16 v[136:139], v[192:195], v[152:155], v[136:139]
	v_mfma_f32_16x16x32_bf16 v[132:135], v[214:217], v[152:155], v[132:135]
	v_mfma_f32_16x16x32_bf16 v[116:119], v[192:195], v[160:163], v[116:119]
	v_mfma_f32_16x16x32_bf16 v[112:115], v[214:217], v[160:163], v[112:115]
	v_mfma_f32_16x16x32_bf16 v[96:99], v[192:195], v[176:179], v[96:99]
	v_mfma_f32_16x16x32_bf16 v[92:95], v[214:217], v[176:179], v[92:95]
	v_mfma_f32_16x16x32_bf16 v[76:79], v[192:195], v[184:187], v[76:79]
	v_mfma_f32_16x16x32_bf16 v[72:75], v[214:217], v[184:187], v[72:75]
	s_setprio 0
	s_mov_b32 m0, s56
	s_barrier
	ds_read_b128 v[148:151], v3 offset:16384
	ds_read_b128 v[152:155], v3 offset:17408
	ds_read_b128 v[156:159], v3 offset:18432
	ds_read_b128 v[160:163], v3 offset:19456
	ds_read_b128 v[172:175], v3 offset:20480
	ds_read_b128 v[176:179], v3 offset:21504
	ds_read_b128 v[180:183], v3 offset:22528
	ds_read_b128 v[184:187], v3 offset:23552
	s_nop 0
	v_lshl_add_u64 v[218:219], s[46:47], 0, v[164:165]
	global_load_lds_dwordx4 v[218:219], off
	v_lshl_add_u64 v[218:219], s[46:47], 0, v[168:169]
	s_mov_b32 m0, s57
	s_nop 0
	global_load_lds_dwordx4 v[218:219], off
	s_barrier
	s_waitcnt lgkmcnt(0)
	s_setprio 1
	s_waitcnt lgkmcnt(0)
	v_mfma_f32_16x16x32_bf16 v[64:67], v[68:71], v[148:151], v[64:67]
	v_mfma_f32_16x16x32_bf16 v[60:63], v[108:111], v[148:151], v[60:63]
	v_mfma_f32_16x16x32_bf16 v[48:51], v[68:71], v[156:159], v[48:51]
	v_mfma_f32_16x16x32_bf16 v[44:47], v[108:111], v[156:159], v[44:47]
	v_mfma_f32_16x16x32_bf16 v[32:35], v[68:71], v[172:175], v[32:35]
	v_mfma_f32_16x16x32_bf16 v[28:31], v[108:111], v[172:175], v[28:31]
	v_mfma_f32_16x16x32_bf16 v[16:19], v[68:71], v[180:183], v[16:19]
	v_mfma_f32_16x16x32_bf16 v[12:15], v[108:111], v[180:183], v[12:15]
	v_mfma_f32_16x16x32_bf16 v[64:67], v[88:91], v[152:155], v[64:67]
	v_mfma_f32_16x16x32_bf16 v[60:63], v[128:131], v[152:155], v[60:63]
	v_mfma_f32_16x16x32_bf16 v[48:51], v[88:91], v[160:163], v[48:51]
	v_mfma_f32_16x16x32_bf16 v[44:47], v[128:131], v[160:163], v[44:47]
	v_mfma_f32_16x16x32_bf16 v[32:35], v[88:91], v[176:179], v[32:35]
	v_mfma_f32_16x16x32_bf16 v[28:31], v[128:131], v[176:179], v[28:31]
	v_mfma_f32_16x16x32_bf16 v[16:19], v[88:91], v[184:187], v[16:19]
	v_mfma_f32_16x16x32_bf16 v[12:15], v[128:131], v[184:187], v[12:15]
	s_setprio 0
	s_barrier
	s_mov_b32 m0, s79
	s_nop 0
	v_lshl_add_u64 v[68:69], s[44:45], 0, v[166:167]
	global_load_lds_dwordx4 v[68:69], off
	v_lshl_add_u64 v[68:69], s[44:45], 0, v[170:171]
	s_mov_b32 m0, s75
	s_nop 0
	global_load_lds_dwordx4 v[68:69], off
	s_waitcnt vmcnt(6)
	s_barrier
	s_setprio 1
	v_mfma_f32_16x16x32_bf16 v[56:59], v[188:191], v[148:151], v[56:59]
	v_mfma_f32_16x16x32_bf16 v[52:55], v[210:213], v[148:151], v[52:55]
	v_mfma_f32_16x16x32_bf16 v[40:43], v[188:191], v[156:159], v[40:43]
	v_mfma_f32_16x16x32_bf16 v[36:39], v[210:213], v[156:159], v[36:39]
	v_mfma_f32_16x16x32_bf16 v[24:27], v[188:191], v[172:175], v[24:27]
	v_mfma_f32_16x16x32_bf16 v[20:23], v[210:213], v[172:175], v[20:23]
	v_mfma_f32_16x16x32_bf16 v[8:11], v[188:191], v[180:183], v[8:11]
	v_mfma_f32_16x16x32_bf16 v[4:7], v[210:213], v[180:183], v[4:7]
	v_mfma_f32_16x16x32_bf16 v[56:59], v[192:195], v[152:155], v[56:59]
	v_mfma_f32_16x16x32_bf16 v[52:55], v[214:217], v[152:155], v[52:55]
	v_mfma_f32_16x16x32_bf16 v[40:43], v[192:195], v[160:163], v[40:43]
	v_mfma_f32_16x16x32_bf16 v[36:39], v[214:217], v[160:163], v[36:39]
	v_mfma_f32_16x16x32_bf16 v[24:27], v[192:195], v[176:179], v[24:27]
	v_mfma_f32_16x16x32_bf16 v[20:23], v[214:217], v[176:179], v[20:23]
	v_mfma_f32_16x16x32_bf16 v[8:11], v[192:195], v[184:187], v[8:11]
	v_mfma_f32_16x16x32_bf16 v[4:7], v[214:217], v[184:187], v[4:7]
	s_setprio 0
	v_add_u32_e32 v128, s74, v1
	s_barrier
	ds_read_b128 v[68:71], v128
	ds_read_b128 v[88:91], v128 offset:1024
	ds_read_b128 v[108:111], v128 offset:2048
	ds_read_b128 v[128:131], v128 offset:3072
	s_mov_b32 m0, s62
	ds_read_b128 v[148:151], v3 offset:32768
	ds_read_b128 v[152:155], v3 offset:33792
	ds_read_b128 v[156:159], v3 offset:34816
	ds_read_b128 v[160:163], v3 offset:35840
	ds_read_b128 v[172:175], v3 offset:36864
	ds_read_b128 v[176:179], v3 offset:37888
	ds_read_b128 v[180:183], v3 offset:38912
	ds_read_b128 v[184:187], v3 offset:39936
	s_nop 0
	v_lshl_add_u64 v[188:189], s[42:43], 0, v[164:165]
	global_load_lds_dwordx4 v[188:189], off
	v_lshl_add_u64 v[188:189], s[42:43], 0, v[168:169]
	s_mov_b32 m0, s63
	s_nop 0
	global_load_lds_dwordx4 v[188:189], off
	s_waitcnt lgkmcnt(8)
	s_barrier
	s_waitcnt lgkmcnt(0)
	s_setprio 1
	s_waitcnt lgkmcnt(0)
	v_mfma_f32_16x16x32_bf16 v[144:147], v[68:71], v[148:151], v[144:147]
	v_mfma_f32_16x16x32_bf16 v[140:143], v[108:111], v[148:151], v[140:143]
	v_mfma_f32_16x16x32_bf16 v[124:127], v[68:71], v[156:159], v[124:127]
	v_mfma_f32_16x16x32_bf16 v[120:123], v[108:111], v[156:159], v[120:123]
	v_mfma_f32_16x16x32_bf16 v[104:107], v[68:71], v[172:175], v[104:107]
	v_mfma_f32_16x16x32_bf16 v[100:103], v[108:111], v[172:175], v[100:103]
	v_mfma_f32_16x16x32_bf16 v[84:87], v[68:71], v[180:183], v[84:87]
	v_mfma_f32_16x16x32_bf16 v[80:83], v[108:111], v[180:183], v[80:83]
	v_mfma_f32_16x16x32_bf16 v[144:147], v[88:91], v[152:155], v[144:147]
	v_mfma_f32_16x16x32_bf16 v[140:143], v[128:131], v[152:155], v[140:143]
	v_mfma_f32_16x16x32_bf16 v[124:127], v[88:91], v[160:163], v[124:127]
	v_mfma_f32_16x16x32_bf16 v[120:123], v[128:131], v[160:163], v[120:123]
	v_mfma_f32_16x16x32_bf16 v[104:107], v[88:91], v[176:179], v[104:107]
	v_mfma_f32_16x16x32_bf16 v[100:103], v[128:131], v[176:179], v[100:103]
	v_mfma_f32_16x16x32_bf16 v[84:87], v[88:91], v[184:187], v[84:87]
	v_mfma_f32_16x16x32_bf16 v[80:83], v[128:131], v[184:187], v[80:83]
	s_setprio 0
	s_barrier
	v_add_u32_e32 v214, s67, v1
	s_mov_b32 m0, s68
	ds_read_b128 v[188:191], v214
	ds_read_b128 v[192:195], v214 offset:1024
	ds_read_b128 v[210:213], v214 offset:2048
	ds_read_b128 v[214:217], v214 offset:3072
	s_nop 0
	v_lshl_add_u64 v[218:219], s[40:41], 0, v[166:167]
	global_load_lds_dwordx4 v[218:219], off
	v_lshl_add_u64 v[218:219], s[40:41], 0, v[170:171]
	s_mov_b32 m0, s29
	s_nop 0
	global_load_lds_dwordx4 v[218:219], off
	s_barrier
	s_waitcnt lgkmcnt(0)
	s_setprio 1
	s_waitcnt lgkmcnt(0)
	v_mfma_f32_16x16x32_bf16 v[136:139], v[188:191], v[148:151], v[136:139]
	v_mfma_f32_16x16x32_bf16 v[132:135], v[210:213], v[148:151], v[132:135]
	v_mfma_f32_16x16x32_bf16 v[116:119], v[188:191], v[156:159], v[116:119]
	v_mfma_f32_16x16x32_bf16 v[112:115], v[210:213], v[156:159], v[112:115]
	v_mfma_f32_16x16x32_bf16 v[96:99], v[188:191], v[172:175], v[96:99]
	v_mfma_f32_16x16x32_bf16 v[92:95], v[210:213], v[172:175], v[92:95]
	v_mfma_f32_16x16x32_bf16 v[76:79], v[188:191], v[180:183], v[76:79]
	v_mfma_f32_16x16x32_bf16 v[72:75], v[210:213], v[180:183], v[72:75]
	v_mfma_f32_16x16x32_bf16 v[136:139], v[192:195], v[152:155], v[136:139]
	v_mfma_f32_16x16x32_bf16 v[132:135], v[214:217], v[152:155], v[132:135]
	v_mfma_f32_16x16x32_bf16 v[116:119], v[192:195], v[160:163], v[116:119]
	v_mfma_f32_16x16x32_bf16 v[112:115], v[214:217], v[160:163], v[112:115]
	v_mfma_f32_16x16x32_bf16 v[96:99], v[192:195], v[176:179], v[96:99]
	v_mfma_f32_16x16x32_bf16 v[92:95], v[214:217], v[176:179], v[92:95]
	v_mfma_f32_16x16x32_bf16 v[76:79], v[192:195], v[184:187], v[76:79]
	v_mfma_f32_16x16x32_bf16 v[72:75], v[214:217], v[184:187], v[72:75]
	s_setprio 0
	s_mov_b32 m0, s64
	s_barrier
	ds_read_b128 v[148:151], v3 offset:49152
	ds_read_b128 v[152:155], v3 offset:50176
	ds_read_b128 v[156:159], v3 offset:51200
	ds_read_b128 v[160:163], v3 offset:52224
	ds_read_b128 v[172:175], v3 offset:53248
	ds_read_b128 v[176:179], v3 offset:54272
	ds_read_b128 v[180:183], v3 offset:55296
	ds_read_b128 v[184:187], v3 offset:56320
	s_nop 0
	v_lshl_add_u64 v[218:219], s[36:37], 0, v[164:165]
	global_load_lds_dwordx4 v[218:219], off
	v_lshl_add_u64 v[218:219], s[36:37], 0, v[168:169]
	s_mov_b32 m0, s65
	s_nop 0
	global_load_lds_dwordx4 v[218:219], off
	s_barrier
	s_waitcnt lgkmcnt(0)
	s_setprio 1
	s_waitcnt lgkmcnt(0)
	v_mfma_f32_16x16x32_bf16 v[64:67], v[68:71], v[148:151], v[64:67]
	v_mfma_f32_16x16x32_bf16 v[60:63], v[108:111], v[148:151], v[60:63]
	v_mfma_f32_16x16x32_bf16 v[48:51], v[68:71], v[156:159], v[48:51]
	v_mfma_f32_16x16x32_bf16 v[44:47], v[108:111], v[156:159], v[44:47]
	v_mfma_f32_16x16x32_bf16 v[32:35], v[68:71], v[172:175], v[32:35]
	v_mfma_f32_16x16x32_bf16 v[28:31], v[108:111], v[172:175], v[28:31]
	v_mfma_f32_16x16x32_bf16 v[16:19], v[68:71], v[180:183], v[16:19]
	v_mfma_f32_16x16x32_bf16 v[12:15], v[108:111], v[180:183], v[12:15]
	v_mfma_f32_16x16x32_bf16 v[64:67], v[88:91], v[152:155], v[64:67]
	v_mfma_f32_16x16x32_bf16 v[60:63], v[128:131], v[152:155], v[60:63]
	v_mfma_f32_16x16x32_bf16 v[48:51], v[88:91], v[160:163], v[48:51]
	v_mfma_f32_16x16x32_bf16 v[44:47], v[128:131], v[160:163], v[44:47]
	v_mfma_f32_16x16x32_bf16 v[32:35], v[88:91], v[176:179], v[32:35]
	v_mfma_f32_16x16x32_bf16 v[28:31], v[128:131], v[176:179], v[28:31]
	v_mfma_f32_16x16x32_bf16 v[16:19], v[88:91], v[184:187], v[16:19]
	v_mfma_f32_16x16x32_bf16 v[12:15], v[128:131], v[184:187], v[12:15]
	s_setprio 0
	s_barrier
	s_mov_b32 m0, s80
	s_nop 0
	v_lshl_add_u64 v[68:69], s[38:39], 0, v[166:167]
	global_load_lds_dwordx4 v[68:69], off
	v_lshl_add_u64 v[68:69], s[38:39], 0, v[170:171]
	s_mov_b32 m0, s78
	s_nop 0
	global_load_lds_dwordx4 v[68:69], off
	s_waitcnt vmcnt(6)
	s_barrier
	s_setprio 1
	v_mfma_f32_16x16x32_bf16 v[56:59], v[188:191], v[148:151], v[56:59]
	v_mfma_f32_16x16x32_bf16 v[52:55], v[210:213], v[148:151], v[52:55]
	v_mfma_f32_16x16x32_bf16 v[40:43], v[188:191], v[156:159], v[40:43]
	v_mfma_f32_16x16x32_bf16 v[36:39], v[210:213], v[156:159], v[36:39]
	v_mfma_f32_16x16x32_bf16 v[24:27], v[188:191], v[172:175], v[24:27]
	v_mfma_f32_16x16x32_bf16 v[20:23], v[210:213], v[172:175], v[20:23]
	v_mfma_f32_16x16x32_bf16 v[8:11], v[188:191], v[180:183], v[8:11]
	v_mfma_f32_16x16x32_bf16 v[4:7], v[210:213], v[180:183], v[4:7]
	v_mfma_f32_16x16x32_bf16 v[56:59], v[192:195], v[152:155], v[56:59]
	v_mfma_f32_16x16x32_bf16 v[52:55], v[214:217], v[152:155], v[52:55]
	v_mfma_f32_16x16x32_bf16 v[40:43], v[192:195], v[160:163], v[40:43]
	v_mfma_f32_16x16x32_bf16 v[36:39], v[214:217], v[160:163], v[36:39]
	v_mfma_f32_16x16x32_bf16 v[24:27], v[192:195], v[176:179], v[24:27]
	v_mfma_f32_16x16x32_bf16 v[20:23], v[214:217], v[176:179], v[20:23]
	v_mfma_f32_16x16x32_bf16 v[8:11], v[192:195], v[184:187], v[8:11]
	v_mfma_f32_16x16x32_bf16 v[4:7], v[214:217], v[184:187], v[4:7]
	s_setprio 0
	s_andn2_b64 vcc, exec, s[16:17]
	s_mov_b64 s[38:39], -1
	s_mov_b64 s[16:17], 0
	s_mov_b64 s[36:37], 0x100
	s_barrier
	s_cbranch_vccz .LBB0_1012
	v_mov_b32_e32 v68, v0
	s_cmp_gt_i32 s8, 2
	s_cselect_b64 s[0:1], -1, 0
	v_readfirstlane_b32 s9, v68
	s_ashr_i32 s19, s18, 31
	s_lshl_b64 s[16:17], s[18:19], 8
	s_ashr_i32 s18, s9, 2
	s_andn2_b32 s18, s18, 63
	s_ashr_i32 s19, s18, 31
	s_add_u32 s18, s16, s18
	v_bfe_u32 v174, v68, 4, 2
	s_addc_u32 s19, s17, s19
	v_and_or_b32 v172, v68, 15, s18
	v_mov_b32_e32 v173, s19
	v_lshlrev_b32_e32 v179, 3, v174
	s_and_b64 vcc, exec, s[0:1]
	s_cbranch_vccnz .LBB0_1015
	v_mov_b64_e32 v[68:69], s[6:7]
	s_movk_i32 s20, 0x240
	v_mad_u64_u32 v[68:69], s[16:17], v172, s20, v[68:69]
	v_mov_b32_e32 v70, v69
	v_mad_u64_u32 v[70:71], s[16:17], v173, s20, v[70:71]
	v_mov_b32_e32 v69, v70
	v_lshlrev_b32_e32 v70, 1, v179
	v_mov_b32_e32 v71, v2
	v_lshl_add_u64 v[68:69], v[68:69], 0, v[70:71]
	v_add_co_u32_e32 v70, vcc, 0x2000, v68
	s_movk_i32 s16, 0x4000
	s_nop 0
	v_addc_co_u32_e32 v71, vcc, 0, v69, vcc
	global_load_dwordx4 v[160:163], v[68:69], off offset:512
	global_load_dwordx4 v[156:159], v[70:71], off offset:1536
	v_add_co_u32_e32 v70, vcc, s16, v68
	s_nop 1
	v_addc_co_u32_e32 v71, vcc, 0, v69, vcc
	v_add_co_u32_e32 v88, vcc, 0x6000, v68
	s_nop 1
	v_addc_co_u32_e32 v89, vcc, 0, v69, vcc
	global_load_dwordx4 v[152:155], v[70:71], off offset:2560
	global_load_dwordx4 v[148:151], v[88:89], off offset:3584
	v_add_co_u32_e32 v70, vcc, 0x12000, v68
	s_nop 1
	v_addc_co_u32_e32 v71, vcc, 0, v69, vcc
	v_add_co_u32_e32 v88, vcc, 0x14000, v68
	s_nop 1
	v_addc_co_u32_e32 v89, vcc, 0, v69, vcc
	global_load_dwordx4 v[128:131], v[70:71], off offset:512
	global_load_dwordx4 v[108:111], v[88:89], off offset:1536
	v_add_co_u32_e32 v70, vcc, 0x16000, v68
	s_nop 1
	v_addc_co_u32_e32 v71, vcc, 0, v69, vcc
	v_add_co_u32_e32 v68, vcc, 0x18000, v68
	s_nop 1
	v_addc_co_u32_e32 v69, vcc, 0, v69, vcc
	global_load_dwordx4 v[88:91], v[70:71], off offset:2560
	s_nop 0
	global_load_dwordx4 v[68:71], v[68:69], off offset:3584

.LBB0_1747:
	s_mul_hi_i32 s0, s8, 0x2aaaaaab
	s_lshr_b32 s1, s0, 31
	s_ashr_i32 s9, s0, 1
	s_add_i32 s9, s9, s1
	s_mul_i32 s0, s9, 12
	s_sub_i32 s0, s8, s0
	v_add_u32_e32 v4, s0, v1
	v_ashrrev_i32_e32 v5, 31, v4
	v_mad_i64_i32 v[84:85], s[18:19], s9, v234, v[4:5]
	s_mov_b64 s[18:19], 0x60
	v_lshlrev_b64 v[86:87], 3, v[84:85]
	v_lshl_add_u64 v[76:77], v[84:85], 0, s[18:19]
	v_lshl_add_u64 v[4:5], s[14:15], 0, v[86:87]
	v_lshlrev_b64 v[78:79], 3, v[76:77]
	s_barrier
	global_load_dword v22, v[4:5], off
	v_lshl_add_u64 v[4:5], s[14:15], 0, v[78:79]
	global_load_dword v90, v[4:5], off
	s_mov_b32 s1, 0xf149f2ca
	v_lshl_add_u64 v[86:87], s[6:7], 0, v[86:87]
	s_mov_b64 s[18:19], 0xc0
	v_lshl_add_u64 v[72:73], v[84:85], 0, s[18:19]
	v_lshl_add_u64 v[78:79], s[6:7], 0, v[78:79]
	v_lshlrev_b64 v[74:75], 3, v[72:73]
	v_lshl_add_u64 v[4:5], s[14:15], 0, v[74:75]
	s_mov_b64 s[18:19], 0x120
	v_lshl_add_u64 v[74:75], s[6:7], 0, v[74:75]
	v_lshl_add_u64 v[68:69], v[84:85], 0, s[18:19]
	v_lshlrev_b64 v[70:71], 3, v[68:69]
	global_load_dword v91, v[4:5], off
	s_mov_b64 s[18:19], 0x180
	v_lshl_add_u64 v[64:65], v[84:85], 0, s[18:19]
	v_lshlrev_b64 v[66:67], 3, v[64:65]
	s_mov_b64 s[18:19], 0x1e0
	v_lshl_add_u64 v[60:61], v[84:85], 0, s[18:19]
	v_lshlrev_b64 v[62:63], 3, v[60:61]
	s_mov_b64 s[18:19], 0x240
	v_lshl_add_u64 v[56:57], v[84:85], 0, s[18:19]
	s_mov_b64 s[18:19], 0x2a0
	v_lshlrev_b64 v[58:59], 3, v[56:57]
	v_lshl_add_u64 v[52:53], v[84:85], 0, s[18:19]
	s_mov_b64 s[18:19], 0x300
	v_lshlrev_b64 v[54:55], 3, v[52:53]
	v_lshl_add_u64 v[48:49], v[84:85], 0, s[18:19]
	s_mov_b64 s[18:19], 0x360
	v_lshlrev_b64 v[50:51], 3, v[48:49]
	v_lshl_add_u64 v[44:45], v[84:85], 0, s[18:19]
	s_mov_b64 s[18:19], 0x3c0
	v_lshlrev_b64 v[46:47], 3, v[44:45]
	v_lshl_add_u64 v[40:41], v[84:85], 0, s[18:19]
	s_mov_b64 s[18:19], 0x420
	v_lshlrev_b64 v[42:43], 3, v[40:41]
	v_lshl_add_u64 v[36:37], v[84:85], 0, s[18:19]
	s_mov_b64 s[18:19], 0x480
	v_lshlrev_b64 v[38:39], 3, v[36:37]
	v_lshl_add_u64 v[32:33], v[84:85], 0, s[18:19]
	s_mov_b64 s[18:19], 0x4e0
	v_lshlrev_b64 v[34:35], 3, v[32:33]
	v_lshl_add_u64 v[28:29], v[84:85], 0, s[18:19]
	v_lshlrev_b64 v[30:31], 3, v[28:29]
	s_mov_b64 s[18:19], 0x540
	v_lshl_add_u64 v[24:25], v[84:85], 0, s[18:19]
	v_lshlrev_b64 v[26:27], 3, v[24:25]
	s_mov_b64 s[18:19], 0x5a0
	v_lshlrev_b64 v[76:77], 10, v[76:77]
	v_lshl_add_u64 v[76:77], v[16:17], 0, v[76:77]
	v_lshlrev_b64 v[72:73], 10, v[72:73]
	v_lshl_add_u64 v[72:73], v[16:17], 0, v[72:73]
	v_lshlrev_b64 v[68:69], 10, v[68:69]
	v_lshl_add_u64 v[68:69], v[16:17], 0, v[68:69]
	v_lshlrev_b64 v[64:65], 10, v[64:65]
	v_lshl_add_u64 v[64:65], v[16:17], 0, v[64:65]
	v_lshlrev_b64 v[60:61], 10, v[60:61]
	v_lshl_add_u64 v[60:61], v[16:17], 0, v[60:61]
	v_lshlrev_b64 v[56:57], 10, v[56:57]
	v_lshl_add_u64 v[56:57], v[16:17], 0, v[56:57]
	v_lshlrev_b64 v[52:53], 10, v[52:53]
	v_lshl_add_u64 v[52:53], v[16:17], 0, v[52:53]
	v_lshlrev_b64 v[48:49], 10, v[48:49]
	v_lshl_add_u64 v[48:49], v[16:17], 0, v[48:49]
	v_lshlrev_b64 v[44:45], 10, v[44:45]
	v_lshl_add_u64 v[44:45], v[16:17], 0, v[44:45]
	v_lshlrev_b64 v[40:41], 10, v[40:41]
	v_lshl_add_u64 v[40:41], v[16:17], 0, v[40:41]
	v_lshlrev_b64 v[36:37], 10, v[36:37]
	v_lshl_add_u64 v[36:37], v[16:17], 0, v[36:37]
	v_lshlrev_b64 v[32:33], 10, v[32:33]
	v_lshl_add_u64 v[32:33], v[16:17], 0, v[32:33]
	v_lshlrev_b64 v[28:29], 10, v[28:29]
	v_lshl_add_u64 v[28:29], v[16:17], 0, v[28:29]
	v_lshlrev_b64 v[24:25], 10, v[24:25]
	v_lshl_add_u64 v[24:25], v[16:17], 0, v[24:25]
	s_lshl_b32 s0, s0, 6
	s_waitcnt vmcnt(1)
	v_max3_f32 v6, v22, s1, v90
	s_mov_b32 s1, 0x34cd0000
	v_add_co_u32_e32 v86, vcc, s1, v86
	s_nop 1
	v_addc_co_u32_e32 v87, vcc, 0, v87, vcc
	v_add_co_u32_e32 v78, vcc, s1, v78
	global_load_dword v86, v[86:87], off offset:4
	s_nop 0
	v_addc_co_u32_e32 v79, vcc, 0, v79, vcc
	v_add_co_u32_e32 v74, vcc, s1, v74
	global_load_dword v78, v[78:79], off offset:4
	s_nop 0
	v_addc_co_u32_e32 v75, vcc, 0, v75, vcc
	global_load_dword v74, v[74:75], off offset:4
	v_lshl_add_u64 v[4:5], s[14:15], 0, v[70:71]
	v_lshl_add_u64 v[70:71], s[6:7], 0, v[70:71]
	v_add_co_u32_e32 v70, vcc, s1, v70
	global_load_dword v92, v[4:5], off
	s_nop 0
	v_addc_co_u32_e32 v71, vcc, 0, v71, vcc
	global_load_dword v70, v[70:71], off offset:4
	v_lshl_add_u64 v[4:5], s[14:15], 0, v[66:67]
	v_lshl_add_u64 v[66:67], s[6:7], 0, v[66:67]
	v_add_co_u32_e32 v66, vcc, s1, v66
	global_load_dword v93, v[4:5], off
	s_nop 0
	v_addc_co_u32_e32 v67, vcc, 0, v67, vcc
	global_load_dword v66, v[66:67], off offset:4
	v_lshl_add_u64 v[4:5], s[14:15], 0, v[62:63]
	v_lshl_add_u64 v[62:63], s[6:7], 0, v[62:63]
	v_add_co_u32_e32 v62, vcc, s1, v62
	global_load_dword v94, v[4:5], off
	s_nop 0
	v_addc_co_u32_e32 v63, vcc, 0, v63, vcc
	global_load_dword v62, v[62:63], off offset:4
	v_lshl_add_u64 v[4:5], s[14:15], 0, v[58:59]
	global_load_dword v95, v[4:5], off
	v_lshl_add_u64 v[4:5], s[14:15], 0, v[54:55]
	global_load_dword v96, v[4:5], off
	v_lshl_add_u64 v[4:5], s[14:15], 0, v[50:51]
	global_load_dword v97, v[4:5], off
	v_lshl_add_u64 v[4:5], s[14:15], 0, v[46:47]
	global_load_dword v83, v[4:5], off
	v_lshl_add_u64 v[4:5], s[14:15], 0, v[42:43]
	global_load_dword v82, v[4:5], off
	v_lshl_add_u64 v[4:5], s[14:15], 0, v[38:39]
	global_load_dword v81, v[4:5], off
	v_lshl_add_u64 v[4:5], s[14:15], 0, v[34:35]
	global_load_dword v80, v[4:5], off
	v_lshl_add_u64 v[4:5], s[14:15], 0, v[30:31]
	global_load_dword v23, v[4:5], off
	v_lshl_add_u64 v[4:5], s[14:15], 0, v[26:27]
	global_load_dword v21, v[4:5], off
	v_lshl_add_u64 v[4:5], v[84:85], 0, s[18:19]
	v_lshlrev_b64 v[84:85], 10, v[84:85]
	v_lshl_add_u64 v[84:85], v[16:17], 0, v[84:85]
	v_lshl_add_u64 v[58:59], s[6:7], 0, v[58:59]
	v_add_co_u32_e32 v58, vcc, s1, v58
	v_lshl_add_u64 v[54:55], s[6:7], 0, v[54:55]
	s_nop 0
	v_addc_co_u32_e32 v59, vcc, 0, v59, vcc
	v_add_co_u32_e32 v54, vcc, s1, v54
	v_lshl_add_u64 v[50:51], s[6:7], 0, v[50:51]
	s_nop 0
	v_addc_co_u32_e32 v55, vcc, 0, v55, vcc
	v_add_co_u32_e32 v50, vcc, s1, v50
	v_lshl_add_u64 v[46:47], s[6:7], 0, v[46:47]
	s_nop 0
	v_addc_co_u32_e32 v51, vcc, 0, v51, vcc
	v_add_co_u32_e32 v46, vcc, s1, v46
	v_lshl_add_u64 v[42:43], s[6:7], 0, v[42:43]
	s_nop 0
	v_addc_co_u32_e32 v47, vcc, 0, v47, vcc
	v_add_co_u32_e32 v42, vcc, s1, v42
	v_lshl_add_u64 v[38:39], s[6:7], 0, v[38:39]
	s_nop 0
	v_addc_co_u32_e32 v43, vcc, 0, v43, vcc
	v_add_co_u32_e32 v38, vcc, s1, v38
	v_lshl_add_u64 v[34:35], s[6:7], 0, v[34:35]
	s_nop 0
	v_addc_co_u32_e32 v39, vcc, 0, v39, vcc
	v_add_co_u32_e32 v34, vcc, s1, v34
	v_lshl_add_u64 v[30:31], s[6:7], 0, v[30:31]
	s_nop 0
	v_addc_co_u32_e32 v35, vcc, 0, v35, vcc
	v_add_co_u32_e32 v30, vcc, s1, v30
	v_lshl_add_u64 v[26:27], s[6:7], 0, v[26:27]
	s_waitcnt vmcnt(14)
	v_max3_f32 v6, v6, v91, v92
	v_addc_co_u32_e32 v31, vcc, 0, v31, vcc
	v_add_co_u32_e32 v26, vcc, s1, v26
	s_waitcnt vmcnt(10)
	v_max3_f32 v6, v6, v93, v94
	v_addc_co_u32_e32 v27, vcc, 0, v27, vcc
	s_waitcnt vmcnt(7)
	v_max3_f32 v6, v6, v95, v96
	s_waitcnt vmcnt(5)
	v_max3_f32 v6, v6, v97, v83
	s_waitcnt vmcnt(3)
	v_max3_f32 v6, v6, v82, v81
	s_waitcnt vmcnt(1)
	v_max3_f32 v13, v6, v80, v23
	v_lshlrev_b64 v[6:7], 3, v[4:5]
	v_lshl_add_u64 v[88:89], s[14:15], 0, v[6:7]
	global_load_dword v11, v[88:89], off
	v_lshl_add_u64 v[6:7], s[6:7], 0, v[6:7]
	v_add_co_u32_e32 v6, vcc, s1, v6
	v_lshlrev_b64 v[4:5], 10, v[4:5]
	s_nop 0
	v_addc_co_u32_e32 v7, vcc, 0, v7, vcc
	v_lshl_add_u64 v[4:5], v[16:17], 0, v[4:5]
	s_ashr_i32 s1, s0, 31
	s_waitcnt vmcnt(0)
	v_max3_f32 v13, v13, v21, v11
	v_sub_f32_e32 v22, v22, v13
	v_exp_f32_e32 v88, v22
	v_sub_f32_e32 v23, v23, v13
	v_sub_f32_e32 v21, v21, v13
	v_sub_f32_e32 v11, v11, v13
	v_fma_f32 v89, v86, v88, 0
	global_load_dwordx4 v[84:87], v[84:85], off
	global_load_dwordx4 v[162:165], v[76:77], off
	global_load_dwordx4 v[166:169], v[72:73], off
	global_load_dwordx4 v[170:173], v[68:69], off
	global_load_dwordx4 v[174:177], v[64:65], off
	global_load_dwordx4 v[178:181], v[60:61], off
	global_load_dwordx4 v[182:185], v[56:57], off
	global_load_dwordx4 v[186:189], v[52:53], off
	global_load_dwordx4 v[190:193], v[48:49], off
	global_load_dwordx4 v[194:197], v[44:45], off
	global_load_dwordx4 v[204:207], v[40:41], off
	global_load_dwordx4 v[210:213], v[36:37], off
	global_load_dwordx4 v[214:217], v[32:33], off
	global_load_dwordx4 v[218:221], v[28:29], off
	global_load_dwordx4 v[222:225], v[24:25], off
	global_load_dwordx4 v[226:229], v[4:5], off
	global_load_dword v248, v[58:59], off offset:4
	global_load_dword v249, v[54:55], off offset:4
	global_load_dword v250, v[50:51], off offset:4
	global_load_dword v251, v[46:47], off offset:4
	global_load_dword v232, v[42:43], off offset:4
	global_load_dword v233, v[38:39], off offset:4
	global_load_dword v198, v[34:35], off offset:4
	global_load_dword v199, v[30:31], off offset:4
	global_load_dword v244, v[26:27], off offset:4
	global_load_dword v245, v[6:7], off offset:4
	v_mov_b32_e32 v22, 0
	s_waitcnt vmcnt(0)
	v_pk_fma_f32 v[86:87], v[86:87], v[88:89], 0 op_sel_hi:[1,0,0]
	v_pk_fma_f32 v[84:85], v[84:85], v[88:89], 0 op_sel_hi:[1,0,0]
	v_sub_f32_e32 v88, v90, v13
	v_exp_f32_e32 v88, v88
	s_nop 0
	v_fmac_f32_e32 v89, v88, v78
	s_nop 0
	v_pk_fma_f32 v[76:77], v[162:163], v[88:89], v[84:85] op_sel_hi:[1,0,1]
	v_sub_f32_e32 v84, v91, v13
	v_exp_f32_e32 v84, v84
	v_pk_fma_f32 v[78:79], v[164:165], v[88:89], v[86:87] op_sel_hi:[1,0,1]
	v_fmac_f32_e32 v89, v84, v74
	s_nop 0
	v_pk_fma_f32 v[72:73], v[84:85], v[166:167], v[76:77] op_sel_hi:[0,1,1]
	v_sub_f32_e32 v76, v92, v13
	v_exp_f32_e32 v76, v76
	v_pk_fma_f32 v[74:75], v[84:85], v[168:169], v[78:79] op_sel_hi:[0,1,1]
	v_fmac_f32_e32 v89, v76, v70
	s_nop 0
	v_pk_fma_f32 v[68:69], v[76:77], v[170:171], v[72:73] op_sel_hi:[0,1,1]
	v_sub_f32_e32 v72, v93, v13
	v_exp_f32_e32 v72, v72
	v_pk_fma_f32 v[70:71], v[76:77], v[172:173], v[74:75] op_sel_hi:[0,1,1]
	v_fmac_f32_e32 v89, v72, v66
	s_nop 0
	v_pk_fma_f32 v[64:65], v[72:73], v[174:175], v[68:69] op_sel_hi:[0,1,1]
	v_sub_f32_e32 v68, v94, v13
	v_exp_f32_e32 v68, v68
	v_pk_fma_f32 v[66:67], v[72:73], v[176:177], v[70:71] op_sel_hi:[0,1,1]
	v_fmac_f32_e32 v89, v68, v62
	s_nop 0
	v_pk_fma_f32 v[62:63], v[68:69], v[180:181], v[66:67] op_sel_hi:[0,1,1]
	v_pk_fma_f32 v[60:61], v[68:69], v[178:179], v[64:65] op_sel_hi:[0,1,1]
	v_sub_f32_e32 v64, v95, v13
	v_exp_f32_e32 v64, v64
	s_nop 0
	v_pk_fma_f32 v[56:57], v[64:65], v[182:183], v[60:61] op_sel_hi:[0,1,1]
	v_sub_f32_e32 v60, v96, v13
	v_pk_fma_f32 v[58:59], v[64:65], v[184:185], v[62:63] op_sel_hi:[0,1,1]
	v_exp_f32_e32 v65, v60
	s_nop 0
	v_pk_mul_f32 v[54:55], v[64:65], v[248:249]
	s_nop 0
	v_add_f32_e32 v54, v89, v54
	v_add_f32_e32 v61, v54, v55
	v_mov_b32_e32 v60, v65
	s_nop 0
	v_pk_fma_f32 v[54:55], v[60:61], v[188:189], v[58:59] op_sel_hi:[0,1,1]
	v_pk_fma_f32 v[52:53], v[60:61], v[186:187], v[56:57] op_sel_hi:[0,1,1]
	v_sub_f32_e32 v56, v97, v13
	v_exp_f32_e32 v56, v56
	s_nop 0
	v_pk_fma_f32 v[48:49], v[56:57], v[190:191], v[52:53] op_sel_hi:[0,1,1]
	v_sub_f32_e32 v52, v83, v13
	v_pk_fma_f32 v[50:51], v[56:57], v[192:193], v[54:55] op_sel_hi:[0,1,1]
	v_exp_f32_e32 v57, v52
	s_nop 0
	v_pk_mul_f32 v[46:47], v[56:57], v[250:251]
	s_nop 0
	v_add_f32_e32 v46, v61, v46
	v_add_f32_e32 v53, v46, v47
	v_mov_b32_e32 v52, v57
	s_nop 0
	v_pk_fma_f32 v[46:47], v[52:53], v[196:197], v[50:51] op_sel_hi:[0,1,1]
	v_pk_fma_f32 v[44:45], v[52:53], v[194:195], v[48:49] op_sel_hi:[0,1,1]
	v_sub_f32_e32 v48, v82, v13
	v_exp_f32_e32 v48, v48
	s_nop 0
	v_pk_fma_f32 v[40:41], v[48:49], v[204:205], v[44:45] op_sel_hi:[0,1,1]
	v_sub_f32_e32 v44, v81, v13
	v_pk_fma_f32 v[42:43], v[48:49], v[206:207], v[46:47] op_sel_hi:[0,1,1]
	v_exp_f32_e32 v49, v44
	s_nop 0
	v_pk_mul_f32 v[38:39], v[48:49], v[232:233]
	s_nop 0
	v_add_f32_e32 v38, v53, v38
	v_add_f32_e32 v45, v38, v39
	v_mov_b32_e32 v44, v49
	s_nop 0
	v_pk_fma_f32 v[38:39], v[44:45], v[212:213], v[42:43] op_sel_hi:[0,1,1]
	v_pk_fma_f32 v[36:37], v[44:45], v[210:211], v[40:41] op_sel_hi:[0,1,1]
	v_sub_f32_e32 v40, v80, v13
	v_exp_f32_e32 v40, v40
	s_nop 0
	v_pk_fma_f32 v[34:35], v[40:41], v[216:217], v[38:39] op_sel_hi:[0,1,1]
	v_pk_fma_f32 v[32:33], v[40:41], v[214:215], v[36:37] op_sel_hi:[0,1,1]
	v_exp_f32_e32 v41, v23
	s_nop 0
	v_pk_mul_f32 v[30:31], v[40:41], v[198:199]
	s_nop 0
	v_add_f32_e32 v23, v45, v30
	v_add_f32_e32 v23, v23, v31
	v_mov_b32_e32 v36, v41
	s_nop 0
	v_pk_fma_f32 v[30:31], v[36:37], v[220:221], v[34:35] op_sel_hi:[0,1,1]
	v_pk_fma_f32 v[28:29], v[36:37], v[218:219], v[32:33] op_sel_hi:[0,1,1]
	v_exp_f32_e32 v32, v21
	s_nop 0
	v_pk_fma_f32 v[26:27], v[32:33], v[224:225], v[30:31] op_sel_hi:[0,1,1]
	v_pk_fma_f32 v[24:25], v[32:33], v[222:223], v[28:29] op_sel_hi:[0,1,1]
	v_exp_f32_e32 v33, v11
	v_mov_b32_e32 v30, v22
	v_mov_b32_e32 v31, v22
	v_pk_mul_f32 v[6:7], v[32:33], v[244:245]
	s_nop 0
	v_add_f32_e32 v6, v23, v6
	v_add_f32_e32 v11, v6, v7
	v_div_scale_f32 v13, s[18:19], v11, v11, 1.0
	v_rcp_f32_e32 v21, v13
	v_mov_b32_e32 v28, v33
	s_mov_b32 s18, -4
	v_fma_f32 v23, -v13, v21, 1.0
	v_fmac_f32_e32 v21, v23, v21
	v_div_scale_f32 v23, vcc, 1.0, v11, 1.0
	s_nop 0
	v_pk_fma_f32 v[4:5], v[28:29], v[226:227], v[24:25] op_sel_hi:[0,1,1]
	v_mul_f32_e32 v24, v23, v21
	v_fma_f32 v25, -v13, v24, v23
	v_fmac_f32_e32 v24, v25, v21
	v_fma_f32 v13, -v13, v24, v23
	v_div_fmas_f32 v13, v13, v21, v24
	v_pk_fma_f32 v[6:7], v[28:29], v[228:229], v[26:27] op_sel_hi:[0,1,1]
	v_div_fixup_f32 v24, v13, v11, 1.0
	v_pk_mul_f32 v[6:7], v[6:7], v[24:25] op_sel_hi:[1,0]
	v_pk_mul_f32 v[4:5], v[4:5], v[24:25] op_sel_hi:[1,0]
	v_add_u32_e32 v11, v8, v10
	ds_write_b128 v11, v[4:7]
	v_lshl_add_u64 v[24:25], s[0:1], 2, v[18:19]
	s_mov_b32 s100, 0xffffb800
	s_mov_b32 s101, -1
	v_lshl_add_u64 v[194:195], v[24:25], 0, s[100:101]
	s_mov_b32 s100, 0x2400
	s_mov_b32 s101, 0
	global_load_dword v162, v[194:195], off offset:-3072
	global_load_dword v163, v[194:195], off
	global_load_dword v164, v[194:195], off offset:3072
	v_lshl_add_u64 v[194:195], v[194:195], 0, s[100:101]
	global_load_dword v165, v[194:195], off offset:-3072
	global_load_dword v166, v[194:195], off
	global_load_dword v167, v[194:195], off offset:3072
	v_lshl_add_u64 v[194:195], v[194:195], 0, s[100:101]
	global_load_dword v168, v[194:195], off offset:-3072
	global_load_dword v169, v[194:195], off
	global_load_dword v170, v[194:195], off offset:3072
	v_lshl_add_u64 v[194:195], v[194:195], 0, s[100:101]
	global_load_dword v171, v[194:195], off offset:-3072
	global_load_dword v172, v[194:195], off
	global_load_dword v173, v[194:195], off offset:3072
	v_lshl_add_u64 v[194:195], v[194:195], 0, s[100:101]
	global_load_dword v174, v[194:195], off offset:-3072
	global_load_dword v175, v[194:195], off
	global_load_dword v176, v[194:195], off offset:3072
	v_lshl_add_u64 v[194:195], v[194:195], 0, s[100:101]
	global_load_dword v177, v[194:195], off offset:-3072
	global_load_dword v178, v[194:195], off
	global_load_dword v179, v[194:195], off offset:3072
	v_lshl_add_u64 v[194:195], v[194:195], 0, s[100:101]
	global_load_dword v180, v[194:195], off offset:-3072
	global_load_dword v181, v[194:195], off
	global_load_dword v182, v[194:195], off offset:3072
	v_lshl_add_u64 v[194:195], v[194:195], 0, s[100:101]
	global_load_dword v183, v[194:195], off offset:-3072
	global_load_dword v184, v[194:195], off
	global_load_dword v185, v[194:195], off offset:3072
	v_lshl_add_u64 v[194:195], v[194:195], 0, s[100:101]
	global_load_dword v186, v[194:195], off offset:-3072
	global_load_dword v187, v[194:195], off
	global_load_dword v188, v[194:195], off offset:3072
	v_lshl_add_u64 v[194:195], v[194:195], 0, s[100:101]
	global_load_dword v189, v[194:195], off offset:-3072
	global_load_dword v190, v[194:195], off
	global_load_dword v191, v[194:195], off offset:3072
	v_lshl_add_u64 v[194:195], v[194:195], 0, s[100:101]
	global_load_dword v192, v[194:195], off offset:-3072
	global_load_dword v193, v[194:195], off
	v_mov_b32_e32 v11, v12
	v_mov_b32_e32 v23, v22
	v_mov_b32_e32 v26, v22
	v_mov_b32_e32 v27, v22
	v_mov_b32_e32 v28, v22
	v_mov_b32_e32 v29, v22
	s_waitcnt lgkmcnt(0)
	s_barrier
.LBB0_1748:
	s_waitcnt vmcnt(0)
	s_nop 0
	v_mov_b32_e32 v40, v162
	s_nop 0
	v_mov_b32_e32 v42, v163
	s_nop 0
	v_mov_b32_e32 v44, v164
	v_mov_b32_e32 v46, v165
	ds_read_b128 v[32:35], v11
	ds_read_b128 v[4:7], v11 offset:16
	ds_read_b128 v[36:39], v11 offset:1024
	s_waitcnt lgkmcnt(2)
	v_mov_b32_e32 v48, v32
	s_waitcnt lgkmcnt(0)
	v_mov_b32_e32 v49, v36
	v_mov_b32_e32 v36, v33
	v_pk_mul_f32 v[32:33], v[42:43], v[36:37] op_sel_hi:[0,1]
	v_mov_b32_e32 v37, v38
	v_mov_b32_e32 v38, v35
	v_mov_b32_e32 v36, v34
	v_pk_fma_f32 v[32:33], v[40:41], v[48:49], v[32:33] op_sel_hi:[0,1,1]
	v_pk_mul_f32 v[34:35], v[46:47], v[38:39] op_sel_hi:[0,1]
	v_pk_fma_f32 v[34:35], v[44:45], v[36:37], v[34:35] op_sel_hi:[0,1,1]
	v_pk_add_f32 v[32:33], v[32:33], v[34:35]
	s_nop 0
	v_pk_add_f32 v[26:27], v[26:27], v[32:33]
	ds_read_b128 v[32:35], v11 offset:2048
	ds_read_b128 v[36:39], v11 offset:3072
	s_waitcnt lgkmcnt(1)
	v_mov_b32_e32 v48, v32
	s_waitcnt lgkmcnt(0)
	v_mov_b32_e32 v49, v36
	v_mov_b32_e32 v36, v33
	v_pk_mul_f32 v[32:33], v[42:43], v[36:37] op_sel_hi:[0,1]
	v_mov_b32_e32 v37, v38
	v_mov_b32_e32 v38, v35
	v_mov_b32_e32 v36, v34
	v_pk_mul_f32 v[34:35], v[46:47], v[38:39] op_sel_hi:[0,1]
	v_pk_fma_f32 v[32:33], v[40:41], v[48:49], v[32:33] op_sel_hi:[0,1,1]
	v_pk_fma_f32 v[34:35], v[44:45], v[36:37], v[34:35] op_sel_hi:[0,1,1]
	v_pk_add_f32 v[32:33], v[32:33], v[34:35]
	s_nop 0
	v_pk_add_f32 v[28:29], v[28:29], v[32:33]
	ds_read_b128 v[32:35], v11 offset:4096
	ds_read_b128 v[36:39], v11 offset:5120
	s_waitcnt lgkmcnt(1)
	v_mov_b32_e32 v48, v32
	s_waitcnt lgkmcnt(0)
	v_mov_b32_e32 v49, v36
	v_mov_b32_e32 v36, v33
	v_pk_mul_f32 v[32:33], v[42:43], v[36:37] op_sel_hi:[0,1]
	v_mov_b32_e32 v37, v38
	v_mov_b32_e32 v38, v35
	v_mov_b32_e32 v36, v34
	v_pk_mul_f32 v[34:35], v[46:47], v[38:39] op_sel_hi:[0,1]
	v_pk_fma_f32 v[32:33], v[40:41], v[48:49], v[32:33] op_sel_hi:[0,1,1]
	v_pk_fma_f32 v[34:35], v[44:45], v[36:37], v[34:35] op_sel_hi:[0,1,1]
	v_pk_add_f32 v[32:33], v[32:33], v[34:35]
	v_mov_b32_e32 v41, v42
	v_pk_add_f32 v[30:31], v[30:31], v[32:33]
	ds_read_b128 v[32:35], v11 offset:6144
	v_mov_b32_e32 v45, v46
	v_mov_b32_e32 v43, v44
	s_waitcnt lgkmcnt(0)
	v_mul_f32_e32 v36, v42, v33
	v_pk_fma_f32 v[36:37], v[40:41], v[32:33], v[36:37] op_sel_hi:[1,1,0]
	v_mul_f32_e32 v32, v46, v35
	v_pk_fma_f32 v[38:39], v[44:45], v[34:35], v[32:33] op_sel_hi:[1,1,0]
	ds_read_b128 v[32:35], v11 offset:7168
	v_mov_b32_e32 v41, v46
	s_waitcnt lgkmcnt(0)
	v_mov_b32_e32 v44, v33
	v_mov_b32_e32 v33, v35
	v_mov_b32_e32 v45, v34
	v_pk_mul_f32 v[32:33], v[40:41], v[32:33]
	s_nop 0
	v_pk_fma_f32 v[32:33], v[42:43], v[44:45], v[32:33]
	v_mov_b32_e32 v44, v4
	v_mov_b32_e32 v37, v32
	v_mov_b32_e32 v39, v33
	v_pk_add_f32 v[32:33], v[36:37], v[38:39]
	s_nop 0
	v_pk_add_f32 v[22:23], v[22:23], v[32:33]
	s_nop 0
	v_mov_b32_e32 v32, v166
	s_nop 0
	v_mov_b32_e32 v34, v167
	s_nop 0
	v_mov_b32_e32 v38, v168
	v_mov_b32_e32 v36, v169
	ds_read_b128 v[40:43], v11 offset:1040
	s_waitcnt lgkmcnt(0)
	v_mov_b32_e32 v45, v40
	v_mov_b32_e32 v40, v5
	v_pk_mul_f32 v[4:5], v[34:35], v[40:41] op_sel_hi:[0,1]
	v_mov_b32_e32 v41, v42
	v_mov_b32_e32 v42, v7
	v_mov_b32_e32 v40, v6
	v_pk_mul_f32 v[6:7], v[36:37], v[42:43] op_sel_hi:[0,1]
	v_pk_fma_f32 v[4:5], v[32:33], v[44:45], v[4:5] op_sel_hi:[0,1,1]
	v_pk_fma_f32 v[6:7], v[38:39], v[40:41], v[6:7] op_sel_hi:[0,1,1]
	v_pk_add_f32 v[4:5], v[4:5], v[6:7]
	s_nop 0
	v_pk_add_f32 v[26:27], v[26:27], v[4:5]
	ds_read_b128 v[4:7], v11 offset:2064
	ds_read_b128 v[40:43], v11 offset:3088
	s_waitcnt lgkmcnt(1)
	v_mov_b32_e32 v44, v4
	s_waitcnt lgkmcnt(0)
	v_mov_b32_e32 v45, v40
	v_mov_b32_e32 v40, v5
	v_pk_mul_f32 v[4:5], v[34:35], v[40:41] op_sel_hi:[0,1]
	v_mov_b32_e32 v41, v42
	v_mov_b32_e32 v42, v7
	v_mov_b32_e32 v40, v6
	v_pk_mul_f32 v[6:7], v[36:37], v[42:43] op_sel_hi:[0,1]
	v_pk_fma_f32 v[4:5], v[32:33], v[44:45], v[4:5] op_sel_hi:[0,1,1]
	v_pk_fma_f32 v[6:7], v[38:39], v[40:41], v[6:7] op_sel_hi:[0,1,1]
	v_pk_add_f32 v[4:5], v[4:5], v[6:7]
	s_nop 0
	v_pk_add_f32 v[28:29], v[28:29], v[4:5]
	ds_read_b128 v[4:7], v11 offset:4112
	ds_read_b128 v[40:43], v11 offset:5136
	s_waitcnt lgkmcnt(1)
	v_mov_b32_e32 v44, v4
	s_waitcnt lgkmcnt(0)
	v_mov_b32_e32 v45, v40
	v_mov_b32_e32 v40, v5
	v_pk_mul_f32 v[4:5], v[34:35], v[40:41] op_sel_hi:[0,1]
	v_mov_b32_e32 v41, v42
	v_mov_b32_e32 v42, v7
	v_mov_b32_e32 v40, v6
	v_pk_mul_f32 v[6:7], v[36:37], v[42:43] op_sel_hi:[0,1]
	v_pk_fma_f32 v[4:5], v[32:33], v[44:45], v[4:5] op_sel_hi:[0,1,1]
	v_pk_fma_f32 v[6:7], v[38:39], v[40:41], v[6:7] op_sel_hi:[0,1,1]
	v_pk_add_f32 v[4:5], v[4:5], v[6:7]
	v_mov_b32_e32 v33, v34
	v_pk_add_f32 v[30:31], v[30:31], v[4:5]
	ds_read_b128 v[4:7], v11 offset:6160
	v_mov_b32_e32 v39, v36
	v_mov_b32_e32 v35, v38
	s_waitcnt lgkmcnt(0)
	v_mul_f32_e32 v40, v34, v5
	v_pk_fma_f32 v[40:41], v[32:33], v[4:5], v[40:41] op_sel_hi:[1,1,0]
	v_mul_f32_e32 v4, v36, v7
	v_pk_fma_f32 v[42:43], v[38:39], v[6:7], v[4:5] op_sel_hi:[1,1,0]
	ds_read_b128 v[4:7], v11 offset:7184
	v_mov_b32_e32 v33, v36
	v_add_u32_e32 v11, 32, v11
	s_waitcnt lgkmcnt(0)
	v_mov_b32_e32 v38, v5
	v_mov_b32_e32 v5, v7
	v_mov_b32_e32 v39, v6
	v_pk_mul_f32 v[4:5], v[32:33], v[4:5]
	s_nop 0
	v_pk_fma_f32 v[4:5], v[34:35], v[38:39], v[4:5]
	s_nop 0
	v_mov_b32_e32 v41, v4
	v_mov_b32_e32 v43, v5
	v_pk_add_f32 v[4:5], v[40:41], v[42:43]
	s_nop 0
	v_pk_add_f32 v[22:23], v[22:23], v[4:5]
	s_nop 0
	v_mov_b32_e32 v40, v170
	s_nop 0
	v_mov_b32_e32 v42, v171
	s_nop 0
	v_mov_b32_e32 v44, v172
	v_mov_b32_e32 v46, v173
	ds_read_b128 v[32:35], v11
	ds_read_b128 v[4:7], v11 offset:16
	ds_read_b128 v[36:39], v11 offset:1024
	s_waitcnt lgkmcnt(2)
	v_mov_b32_e32 v48, v32
	s_waitcnt lgkmcnt(0)
	v_mov_b32_e32 v49, v36
	v_mov_b32_e32 v36, v33
	v_pk_mul_f32 v[32:33], v[42:43], v[36:37] op_sel_hi:[0,1]
	v_mov_b32_e32 v37, v38
	v_mov_b32_e32 v38, v35
	v_mov_b32_e32 v36, v34
	v_pk_fma_f32 v[32:33], v[40:41], v[48:49], v[32:33] op_sel_hi:[0,1,1]
	v_pk_mul_f32 v[34:35], v[46:47], v[38:39] op_sel_hi:[0,1]
	v_pk_fma_f32 v[34:35], v[44:45], v[36:37], v[34:35] op_sel_hi:[0,1,1]
	v_pk_add_f32 v[32:33], v[32:33], v[34:35]
	s_nop 0
	v_pk_add_f32 v[26:27], v[26:27], v[32:33]
	ds_read_b128 v[32:35], v11 offset:2048
	ds_read_b128 v[36:39], v11 offset:3072
	s_waitcnt lgkmcnt(1)
	v_mov_b32_e32 v48, v32
	s_waitcnt lgkmcnt(0)
	v_mov_b32_e32 v49, v36
	v_mov_b32_e32 v36, v33
	v_pk_mul_f32 v[32:33], v[42:43], v[36:37] op_sel_hi:[0,1]
	v_mov_b32_e32 v37, v38
	v_mov_b32_e32 v38, v35
	v_mov_b32_e32 v36, v34
	v_pk_mul_f32 v[34:35], v[46:47], v[38:39] op_sel_hi:[0,1]
	v_pk_fma_f32 v[32:33], v[40:41], v[48:49], v[32:33] op_sel_hi:[0,1,1]
	v_pk_fma_f32 v[34:35], v[44:45], v[36:37], v[34:35] op_sel_hi:[0,1,1]
	v_pk_add_f32 v[32:33], v[32:33], v[34:35]
	s_nop 0
	v_pk_add_f32 v[28:29], v[28:29], v[32:33]
	ds_read_b128 v[32:35], v11 offset:4096
	ds_read_b128 v[36:39], v11 offset:5120
	s_waitcnt lgkmcnt(1)
	v_mov_b32_e32 v48, v32
	s_waitcnt lgkmcnt(0)
	v_mov_b32_e32 v49, v36
	v_mov_b32_e32 v36, v33
	v_pk_mul_f32 v[32:33], v[42:43], v[36:37] op_sel_hi:[0,1]
	v_mov_b32_e32 v37, v38
	v_mov_b32_e32 v38, v35
	v_mov_b32_e32 v36, v34
	v_pk_mul_f32 v[34:35], v[46:47], v[38:39] op_sel_hi:[0,1]
	v_pk_fma_f32 v[32:33], v[40:41], v[48:49], v[32:33] op_sel_hi:[0,1,1]
	v_pk_fma_f32 v[34:35], v[44:45], v[36:37], v[34:35] op_sel_hi:[0,1,1]
	v_pk_add_f32 v[32:33], v[32:33], v[34:35]
	v_mov_b32_e32 v41, v42
	v_pk_add_f32 v[30:31], v[30:31], v[32:33]
	ds_read_b128 v[32:35], v11 offset:6144
	v_mov_b32_e32 v45, v46
	v_mov_b32_e32 v43, v44
	s_waitcnt lgkmcnt(0)
	v_mul_f32_e32 v36, v42, v33
	v_pk_fma_f32 v[36:37], v[40:41], v[32:33], v[36:37] op_sel_hi:[1,1,0]
	v_mul_f32_e32 v32, v46, v35
	v_pk_fma_f32 v[38:39], v[44:45], v[34:35], v[32:33] op_sel_hi:[1,1,0]
	ds_read_b128 v[32:35], v11 offset:7168
	v_mov_b32_e32 v41, v46
	s_waitcnt lgkmcnt(0)
	v_mov_b32_e32 v44, v33
	v_mov_b32_e32 v33, v35
	v_mov_b32_e32 v45, v34
	v_pk_mul_f32 v[32:33], v[40:41], v[32:33]
	s_nop 0
	v_pk_fma_f32 v[32:33], v[42:43], v[44:45], v[32:33]
	v_mov_b32_e32 v44, v4
	v_mov_b32_e32 v37, v32
	v_mov_b32_e32 v39, v33
	v_pk_add_f32 v[32:33], v[36:37], v[38:39]
	s_nop 0
	v_pk_add_f32 v[22:23], v[22:23], v[32:33]
	s_nop 0
	v_mov_b32_e32 v32, v174
	s_nop 0
	v_mov_b32_e32 v34, v175
	s_nop 0
	v_mov_b32_e32 v38, v176
	v_mov_b32_e32 v36, v177
	ds_read_b128 v[40:43], v11 offset:1040
	s_waitcnt lgkmcnt(0)
	v_mov_b32_e32 v45, v40
	v_mov_b32_e32 v40, v5
	v_pk_mul_f32 v[4:5], v[34:35], v[40:41] op_sel_hi:[0,1]
	v_mov_b32_e32 v41, v42
	v_mov_b32_e32 v42, v7
	v_mov_b32_e32 v40, v6
	v_pk_mul_f32 v[6:7], v[36:37], v[42:43] op_sel_hi:[0,1]
	v_pk_fma_f32 v[4:5], v[32:33], v[44:45], v[4:5] op_sel_hi:[0,1,1]
	v_pk_fma_f32 v[6:7], v[38:39], v[40:41], v[6:7] op_sel_hi:[0,1,1]
	v_pk_add_f32 v[4:5], v[4:5], v[6:7]
	s_nop 0
	v_pk_add_f32 v[26:27], v[26:27], v[4:5]
	ds_read_b128 v[4:7], v11 offset:2064
	ds_read_b128 v[40:43], v11 offset:3088
	s_waitcnt lgkmcnt(1)
	v_mov_b32_e32 v44, v4
	s_waitcnt lgkmcnt(0)
	v_mov_b32_e32 v45, v40
	v_mov_b32_e32 v40, v5
	v_pk_mul_f32 v[4:5], v[34:35], v[40:41] op_sel_hi:[0,1]
	v_mov_b32_e32 v41, v42
	v_mov_b32_e32 v42, v7
	v_mov_b32_e32 v40, v6
	v_pk_mul_f32 v[6:7], v[36:37], v[42:43] op_sel_hi:[0,1]
	v_pk_fma_f32 v[4:5], v[32:33], v[44:45], v[4:5] op_sel_hi:[0,1,1]
	v_pk_fma_f32 v[6:7], v[38:39], v[40:41], v[6:7] op_sel_hi:[0,1,1]
	v_pk_add_f32 v[4:5], v[4:5], v[6:7]
	s_nop 0
	v_pk_add_f32 v[28:29], v[28:29], v[4:5]
	ds_read_b128 v[4:7], v11 offset:4112
	ds_read_b128 v[40:43], v11 offset:5136
	s_waitcnt lgkmcnt(1)
	v_mov_b32_e32 v44, v4
	s_waitcnt lgkmcnt(0)
	v_mov_b32_e32 v45, v40
	v_mov_b32_e32 v40, v5
	v_pk_mul_f32 v[4:5], v[34:35], v[40:41] op_sel_hi:[0,1]
	v_mov_b32_e32 v41, v42
	v_mov_b32_e32 v42, v7
	v_mov_b32_e32 v40, v6
	v_pk_mul_f32 v[6:7], v[36:37], v[42:43] op_sel_hi:[0,1]
	v_pk_fma_f32 v[4:5], v[32:33], v[44:45], v[4:5] op_sel_hi:[0,1,1]
	v_pk_fma_f32 v[6:7], v[38:39], v[40:41], v[6:7] op_sel_hi:[0,1,1]
	v_pk_add_f32 v[4:5], v[4:5], v[6:7]
	v_mov_b32_e32 v33, v34
	v_pk_add_f32 v[30:31], v[30:31], v[4:5]
	ds_read_b128 v[4:7], v11 offset:6160
	v_mov_b32_e32 v39, v36
	v_mov_b32_e32 v35, v38
	s_waitcnt lgkmcnt(0)
	v_mul_f32_e32 v40, v34, v5
	v_pk_fma_f32 v[40:41], v[32:33], v[4:5], v[40:41] op_sel_hi:[1,1,0]
	v_mul_f32_e32 v4, v36, v7
	v_pk_fma_f32 v[42:43], v[38:39], v[6:7], v[4:5] op_sel_hi:[1,1,0]
	ds_read_b128 v[4:7], v11 offset:7184
	v_mov_b32_e32 v33, v36
	v_add_u32_e32 v11, 32, v11
	s_waitcnt lgkmcnt(0)
	v_mov_b32_e32 v38, v5
	v_mov_b32_e32 v5, v7
	v_mov_b32_e32 v39, v6
	v_pk_mul_f32 v[4:5], v[32:33], v[4:5]
	s_nop 0
	v_pk_fma_f32 v[4:5], v[34:35], v[38:39], v[4:5]
	s_nop 0
	v_mov_b32_e32 v41, v4
	v_mov_b32_e32 v43, v5
	v_pk_add_f32 v[4:5], v[40:41], v[42:43]
	s_nop 0
	v_pk_add_f32 v[22:23], v[22:23], v[4:5]
	s_nop 0
	v_mov_b32_e32 v40, v178
	s_nop 0
	v_mov_b32_e32 v42, v179
	s_nop 0
	v_mov_b32_e32 v44, v180
	v_mov_b32_e32 v46, v181
	ds_read_b128 v[32:35], v11
	ds_read_b128 v[4:7], v11 offset:16
	ds_read_b128 v[36:39], v11 offset:1024
	s_waitcnt lgkmcnt(2)
	v_mov_b32_e32 v48, v32
	s_waitcnt lgkmcnt(0)
	v_mov_b32_e32 v49, v36
	v_mov_b32_e32 v36, v33
	v_pk_mul_f32 v[32:33], v[42:43], v[36:37] op_sel_hi:[0,1]
	v_mov_b32_e32 v37, v38
	v_mov_b32_e32 v38, v35
	v_mov_b32_e32 v36, v34
	v_pk_fma_f32 v[32:33], v[40:41], v[48:49], v[32:33] op_sel_hi:[0,1,1]
	v_pk_mul_f32 v[34:35], v[46:47], v[38:39] op_sel_hi:[0,1]
	v_pk_fma_f32 v[34:35], v[44:45], v[36:37], v[34:35] op_sel_hi:[0,1,1]
	v_pk_add_f32 v[32:33], v[32:33], v[34:35]
	s_nop 0
	v_pk_add_f32 v[26:27], v[26:27], v[32:33]
	ds_read_b128 v[32:35], v11 offset:2048
	ds_read_b128 v[36:39], v11 offset:3072
	s_waitcnt lgkmcnt(1)
	v_mov_b32_e32 v48, v32
	s_waitcnt lgkmcnt(0)
	v_mov_b32_e32 v49, v36
	v_mov_b32_e32 v36, v33
	v_pk_mul_f32 v[32:33], v[42:43], v[36:37] op_sel_hi:[0,1]
	v_mov_b32_e32 v37, v38
	v_mov_b32_e32 v38, v35
	v_mov_b32_e32 v36, v34
	v_pk_mul_f32 v[34:35], v[46:47], v[38:39] op_sel_hi:[0,1]
	v_pk_fma_f32 v[32:33], v[40:41], v[48:49], v[32:33] op_sel_hi:[0,1,1]
	v_pk_fma_f32 v[34:35], v[44:45], v[36:37], v[34:35] op_sel_hi:[0,1,1]
	v_pk_add_f32 v[32:33], v[32:33], v[34:35]
	s_nop 0
	v_pk_add_f32 v[28:29], v[28:29], v[32:33]
	ds_read_b128 v[32:35], v11 offset:4096
	ds_read_b128 v[36:39], v11 offset:5120
	s_waitcnt lgkmcnt(1)
	v_mov_b32_e32 v48, v32
	s_waitcnt lgkmcnt(0)
	v_mov_b32_e32 v49, v36
	v_mov_b32_e32 v36, v33
	v_pk_mul_f32 v[32:33], v[42:43], v[36:37] op_sel_hi:[0,1]
	v_mov_b32_e32 v37, v38
	v_mov_b32_e32 v38, v35
	v_mov_b32_e32 v36, v34
	v_pk_mul_f32 v[34:35], v[46:47], v[38:39] op_sel_hi:[0,1]
	v_pk_fma_f32 v[32:33], v[40:41], v[48:49], v[32:33] op_sel_hi:[0,1,1]
	v_pk_fma_f32 v[34:35], v[44:45], v[36:37], v[34:35] op_sel_hi:[0,1,1]
	v_pk_add_f32 v[32:33], v[32:33], v[34:35]
	v_mov_b32_e32 v41, v42
	v_pk_add_f32 v[30:31], v[30:31], v[32:33]
	ds_read_b128 v[32:35], v11 offset:6144
	v_mov_b32_e32 v45, v46
	v_mov_b32_e32 v43, v44
	s_waitcnt lgkmcnt(0)
	v_mul_f32_e32 v36, v42, v33
	v_pk_fma_f32 v[36:37], v[40:41], v[32:33], v[36:37] op_sel_hi:[1,1,0]
	v_mul_f32_e32 v32, v46, v35
	v_pk_fma_f32 v[38:39], v[44:45], v[34:35], v[32:33] op_sel_hi:[1,1,0]
	ds_read_b128 v[32:35], v11 offset:7168
	v_mov_b32_e32 v41, v46
	s_waitcnt lgkmcnt(0)
	v_mov_b32_e32 v44, v33
	v_mov_b32_e32 v33, v35
	v_mov_b32_e32 v45, v34
	v_pk_mul_f32 v[32:33], v[40:41], v[32:33]
	s_nop 0
	v_pk_fma_f32 v[32:33], v[42:43], v[44:45], v[32:33]
	v_mov_b32_e32 v44, v4
	v_mov_b32_e32 v37, v32
	v_mov_b32_e32 v39, v33
	v_pk_add_f32 v[32:33], v[36:37], v[38:39]
	s_nop 0
	v_pk_add_f32 v[22:23], v[22:23], v[32:33]
	s_nop 0
	v_mov_b32_e32 v32, v182
	s_nop 0
	v_mov_b32_e32 v34, v183
	s_nop 0
	v_mov_b32_e32 v38, v184
	v_mov_b32_e32 v36, v185
	ds_read_b128 v[40:43], v11 offset:1040
	s_waitcnt lgkmcnt(0)
	v_mov_b32_e32 v45, v40
	v_mov_b32_e32 v40, v5
	v_pk_mul_f32 v[4:5], v[34:35], v[40:41] op_sel_hi:[0,1]
	v_mov_b32_e32 v41, v42
	v_mov_b32_e32 v42, v7
	v_mov_b32_e32 v40, v6
	v_pk_mul_f32 v[6:7], v[36:37], v[42:43] op_sel_hi:[0,1]
	v_pk_fma_f32 v[4:5], v[32:33], v[44:45], v[4:5] op_sel_hi:[0,1,1]
	v_pk_fma_f32 v[6:7], v[38:39], v[40:41], v[6:7] op_sel_hi:[0,1,1]
	v_pk_add_f32 v[4:5], v[4:5], v[6:7]
	s_nop 0
	v_pk_add_f32 v[26:27], v[26:27], v[4:5]
	ds_read_b128 v[4:7], v11 offset:2064
	ds_read_b128 v[40:43], v11 offset:3088
	s_waitcnt lgkmcnt(1)
	v_mov_b32_e32 v44, v4
	s_waitcnt lgkmcnt(0)
	v_mov_b32_e32 v45, v40
	v_mov_b32_e32 v40, v5
	v_pk_mul_f32 v[4:5], v[34:35], v[40:41] op_sel_hi:[0,1]
	v_mov_b32_e32 v41, v42
	v_mov_b32_e32 v42, v7
	v_mov_b32_e32 v40, v6
	v_pk_mul_f32 v[6:7], v[36:37], v[42:43] op_sel_hi:[0,1]
	v_pk_fma_f32 v[4:5], v[32:33], v[44:45], v[4:5] op_sel_hi:[0,1,1]
	v_pk_fma_f32 v[6:7], v[38:39], v[40:41], v[6:7] op_sel_hi:[0,1,1]
	v_pk_add_f32 v[4:5], v[4:5], v[6:7]
	s_nop 0
	v_pk_add_f32 v[28:29], v[28:29], v[4:5]
	ds_read_b128 v[4:7], v11 offset:4112
	ds_read_b128 v[40:43], v11 offset:5136
	s_waitcnt lgkmcnt(1)
	v_mov_b32_e32 v44, v4
	s_waitcnt lgkmcnt(0)
	v_mov_b32_e32 v45, v40
	v_mov_b32_e32 v40, v5
	v_pk_mul_f32 v[4:5], v[34:35], v[40:41] op_sel_hi:[0,1]
	v_mov_b32_e32 v41, v42
	v_mov_b32_e32 v42, v7
	v_mov_b32_e32 v40, v6
	v_pk_mul_f32 v[6:7], v[36:37], v[42:43] op_sel_hi:[0,1]
	v_pk_fma_f32 v[4:5], v[32:33], v[44:45], v[4:5] op_sel_hi:[0,1,1]
	v_pk_fma_f32 v[6:7], v[38:39], v[40:41], v[6:7] op_sel_hi:[0,1,1]
	v_pk_add_f32 v[4:5], v[4:5], v[6:7]
	v_mov_b32_e32 v33, v34
	v_pk_add_f32 v[30:31], v[30:31], v[4:5]
	ds_read_b128 v[4:7], v11 offset:6160
	v_mov_b32_e32 v39, v36
	v_mov_b32_e32 v35, v38
	s_waitcnt lgkmcnt(0)
	v_mul_f32_e32 v40, v34, v5
	v_pk_fma_f32 v[40:41], v[32:33], v[4:5], v[40:41] op_sel_hi:[1,1,0]
	v_mul_f32_e32 v4, v36, v7
	v_pk_fma_f32 v[42:43], v[38:39], v[6:7], v[4:5] op_sel_hi:[1,1,0]
	ds_read_b128 v[4:7], v11 offset:7184
	v_mov_b32_e32 v33, v36
	v_add_u32_e32 v11, 32, v11
	s_waitcnt lgkmcnt(0)
	v_mov_b32_e32 v38, v5
	v_mov_b32_e32 v5, v7
	v_mov_b32_e32 v39, v6
	v_pk_mul_f32 v[4:5], v[32:33], v[4:5]
	s_nop 0
	v_pk_fma_f32 v[4:5], v[34:35], v[38:39], v[4:5]
	s_nop 0
	v_mov_b32_e32 v41, v4
	v_mov_b32_e32 v43, v5
	v_pk_add_f32 v[4:5], v[40:41], v[42:43]
	s_nop 0
	v_pk_add_f32 v[22:23], v[22:23], v[4:5]
	s_nop 0
	v_mov_b32_e32 v40, v186
	s_nop 0
	v_mov_b32_e32 v42, v187
	s_nop 0
	v_mov_b32_e32 v44, v188
	v_mov_b32_e32 v46, v189
	ds_read_b128 v[32:35], v11
	ds_read_b128 v[4:7], v11 offset:16
	ds_read_b128 v[36:39], v11 offset:1024
	s_waitcnt lgkmcnt(2)
	v_mov_b32_e32 v48, v32
	s_waitcnt lgkmcnt(0)
	v_mov_b32_e32 v49, v36
	v_mov_b32_e32 v36, v33
	v_pk_mul_f32 v[32:33], v[42:43], v[36:37] op_sel_hi:[0,1]
	v_mov_b32_e32 v37, v38
	v_mov_b32_e32 v38, v35
	v_mov_b32_e32 v36, v34
	v_pk_fma_f32 v[32:33], v[40:41], v[48:49], v[32:33] op_sel_hi:[0,1,1]
	v_pk_mul_f32 v[34:35], v[46:47], v[38:39] op_sel_hi:[0,1]
	v_pk_fma_f32 v[34:35], v[44:45], v[36:37], v[34:35] op_sel_hi:[0,1,1]
	v_pk_add_f32 v[32:33], v[32:33], v[34:35]
	s_nop 0
	v_pk_add_f32 v[26:27], v[26:27], v[32:33]
	ds_read_b128 v[32:35], v11 offset:2048
	ds_read_b128 v[36:39], v11 offset:3072
	s_waitcnt lgkmcnt(1)
	v_mov_b32_e32 v48, v32
	s_waitcnt lgkmcnt(0)
	v_mov_b32_e32 v49, v36
	v_mov_b32_e32 v36, v33
	v_pk_mul_f32 v[32:33], v[42:43], v[36:37] op_sel_hi:[0,1]
	v_mov_b32_e32 v37, v38
	v_mov_b32_e32 v38, v35
	v_mov_b32_e32 v36, v34
	v_pk_mul_f32 v[34:35], v[46:47], v[38:39] op_sel_hi:[0,1]
	v_pk_fma_f32 v[32:33], v[40:41], v[48:49], v[32:33] op_sel_hi:[0,1,1]
	v_pk_fma_f32 v[34:35], v[44:45], v[36:37], v[34:35] op_sel_hi:[0,1,1]
	v_pk_add_f32 v[32:33], v[32:33], v[34:35]
	s_nop 0
	v_pk_add_f32 v[28:29], v[28:29], v[32:33]
	ds_read_b128 v[32:35], v11 offset:4096
	ds_read_b128 v[36:39], v11 offset:5120
	s_waitcnt lgkmcnt(1)
	v_mov_b32_e32 v48, v32
	s_waitcnt lgkmcnt(0)
	v_mov_b32_e32 v49, v36
	v_mov_b32_e32 v36, v33
	v_pk_mul_f32 v[32:33], v[42:43], v[36:37] op_sel_hi:[0,1]
	v_mov_b32_e32 v37, v38
	v_mov_b32_e32 v38, v35
	v_mov_b32_e32 v36, v34
	v_pk_mul_f32 v[34:35], v[46:47], v[38:39] op_sel_hi:[0,1]
	v_pk_fma_f32 v[32:33], v[40:41], v[48:49], v[32:33] op_sel_hi:[0,1,1]
	v_pk_fma_f32 v[34:35], v[44:45], v[36:37], v[34:35] op_sel_hi:[0,1,1]
	v_pk_add_f32 v[32:33], v[32:33], v[34:35]
	v_mov_b32_e32 v41, v42
	v_pk_add_f32 v[30:31], v[30:31], v[32:33]
	ds_read_b128 v[32:35], v11 offset:6144
	v_mov_b32_e32 v45, v46
	v_mov_b32_e32 v43, v44
	s_waitcnt lgkmcnt(0)
	v_mul_f32_e32 v36, v42, v33
	v_pk_fma_f32 v[36:37], v[40:41], v[32:33], v[36:37] op_sel_hi:[1,1,0]
	v_mul_f32_e32 v32, v46, v35
	v_pk_fma_f32 v[38:39], v[44:45], v[34:35], v[32:33] op_sel_hi:[1,1,0]
	ds_read_b128 v[32:35], v11 offset:7168
	v_mov_b32_e32 v41, v46
	s_waitcnt lgkmcnt(0)
	v_mov_b32_e32 v44, v33
	v_mov_b32_e32 v33, v35
	v_mov_b32_e32 v45, v34
	v_pk_mul_f32 v[32:33], v[40:41], v[32:33]
	s_nop 0
	v_pk_fma_f32 v[32:33], v[42:43], v[44:45], v[32:33]
	v_mov_b32_e32 v44, v4
	v_mov_b32_e32 v37, v32
	v_mov_b32_e32 v39, v33
	v_pk_add_f32 v[32:33], v[36:37], v[38:39]
	s_nop 0
	v_pk_add_f32 v[22:23], v[22:23], v[32:33]
	s_nop 0
	v_mov_b32_e32 v32, v190
	s_nop 0
	v_mov_b32_e32 v34, v191
	s_nop 0
	v_mov_b32_e32 v38, v192
	v_mov_b32_e32 v36, v193
	ds_read_b128 v[40:43], v11 offset:1040
	s_waitcnt lgkmcnt(0)
	v_mov_b32_e32 v45, v40
	v_mov_b32_e32 v40, v5
	v_pk_mul_f32 v[4:5], v[34:35], v[40:41] op_sel_hi:[0,1]
	v_mov_b32_e32 v41, v42
	v_mov_b32_e32 v42, v7
	v_mov_b32_e32 v40, v6
	v_pk_mul_f32 v[6:7], v[36:37], v[42:43] op_sel_hi:[0,1]
	v_pk_fma_f32 v[4:5], v[32:33], v[44:45], v[4:5] op_sel_hi:[0,1,1]
	v_pk_fma_f32 v[6:7], v[38:39], v[40:41], v[6:7] op_sel_hi:[0,1,1]
	v_pk_add_f32 v[4:5], v[4:5], v[6:7]
	s_nop 0
	v_pk_add_f32 v[26:27], v[26:27], v[4:5]
	ds_read_b128 v[4:7], v11 offset:2064
	ds_read_b128 v[40:43], v11 offset:3088
	s_waitcnt lgkmcnt(1)
	v_mov_b32_e32 v44, v4
	s_waitcnt lgkmcnt(0)
	v_mov_b32_e32 v45, v40
	v_mov_b32_e32 v40, v5
	v_pk_mul_f32 v[4:5], v[34:35], v[40:41] op_sel_hi:[0,1]
	v_mov_b32_e32 v41, v42
	v_mov_b32_e32 v42, v7
	v_mov_b32_e32 v40, v6
	v_pk_mul_f32 v[6:7], v[36:37], v[42:43] op_sel_hi:[0,1]
	v_pk_fma_f32 v[4:5], v[32:33], v[44:45], v[4:5] op_sel_hi:[0,1,1]
	v_pk_fma_f32 v[6:7], v[38:39], v[40:41], v[6:7] op_sel_hi:[0,1,1]
	v_pk_add_f32 v[4:5], v[4:5], v[6:7]
	s_nop 0
	v_pk_add_f32 v[28:29], v[28:29], v[4:5]
	ds_read_b128 v[4:7], v11 offset:4112
	ds_read_b128 v[40:43], v11 offset:5136
	s_waitcnt lgkmcnt(1)
	v_mov_b32_e32 v44, v4
	s_waitcnt lgkmcnt(0)
	v_mov_b32_e32 v45, v40
	v_mov_b32_e32 v40, v5
	v_pk_mul_f32 v[4:5], v[34:35], v[40:41] op_sel_hi:[0,1]
	v_mov_b32_e32 v41, v42
	v_mov_b32_e32 v42, v7
	v_mov_b32_e32 v40, v6
	v_pk_mul_f32 v[6:7], v[36:37], v[42:43] op_sel_hi:[0,1]
	v_pk_fma_f32 v[4:5], v[32:33], v[44:45], v[4:5] op_sel_hi:[0,1,1]
	v_pk_fma_f32 v[6:7], v[38:39], v[40:41], v[6:7] op_sel_hi:[0,1,1]
	v_pk_add_f32 v[4:5], v[4:5], v[6:7]
	v_mov_b32_e32 v33, v34
	v_pk_add_f32 v[30:31], v[30:31], v[4:5]
	ds_read_b128 v[4:7], v11 offset:6160
	v_mov_b32_e32 v39, v36
	v_mov_b32_e32 v35, v38
	s_waitcnt lgkmcnt(0)
	v_mul_f32_e32 v40, v34, v5
	v_pk_fma_f32 v[40:41], v[32:33], v[4:5], v[40:41] op_sel_hi:[1,1,0]
	v_mul_f32_e32 v4, v36, v7
	v_pk_fma_f32 v[42:43], v[38:39], v[6:7], v[4:5] op_sel_hi:[1,1,0]
	ds_read_b128 v[4:7], v11 offset:7184
	v_mov_b32_e32 v33, v36
	v_add_u32_e32 v11, 32, v11
	s_waitcnt lgkmcnt(0)
	v_mov_b32_e32 v38, v5
	v_mov_b32_e32 v5, v7
	v_mov_b32_e32 v39, v6
	v_pk_mul_f32 v[4:5], v[32:33], v[4:5]
	s_nop 0
	v_pk_fma_f32 v[4:5], v[34:35], v[38:39], v[4:5]
	s_nop 0
	v_mov_b32_e32 v41, v4
	v_mov_b32_e32 v43, v5
	v_pk_add_f32 v[4:5], v[40:41], v[42:43]
	s_nop 0
	v_pk_add_f32 v[22:23], v[22:23], v[4:5]
	ds_write2st64_b32 v9, v26, v27 offset0:32 offset1:33
	ds_write2st64_b32 v9, v28, v29 offset0:34 offset1:35
	ds_write2st64_b32 v9, v30, v31 offset0:36 offset1:37
	ds_write2st64_b32 v9, v22, v23 offset0:38 offset1:39
	s_waitcnt lgkmcnt(0)
	s_barrier
	ds_read2st64_b32 v[4:5], v3 offset0:32 offset1:40
	ds_read2st64_b32 v[6:7], v3 offset0:48 offset1:56
	ds_read2st64_b32 v[22:23], v3 offset0:64 offset1:72
	s_lshl_b32 s18, s9, 3
	s_ashr_i32 s19, s18, 31
	s_waitcnt lgkmcnt(2)
	v_add_f32_e32 v4, 0, v4
	v_add_f32_e32 v11, v4, v5
	ds_read2st64_b32 v[4:5], v3 offset0:80 offset1:88
	s_waitcnt lgkmcnt(2)
	v_add_f32_e32 v6, v11, v6
	v_add_f32_e32 v6, v6, v7
	s_waitcnt lgkmcnt(1)
	v_add_f32_e32 v6, v6, v22
	v_add_f32_e32 v6, v6, v23
	s_waitcnt lgkmcnt(0)
	v_add_f32_e32 v4, v6, v4
	v_add_f32_e32 v4, v4, v5
	v_cvt_pk_bf16_f32 v6, v4, s0
	v_lshl_add_u64 v[4:5], s[18:19], 0, v[14:15]
	v_lshlrev_b64 v[4:5], 11, v[4:5]
	v_lshl_add_u64 v[4:5], s[16:17], 0, v[4:5]
	v_lshl_add_u64 v[4:5], s[0:1], 1, v[4:5]
	v_mov_b32_e32 v21, v2
	s_add_i32 s8, s8, s60
	v_lshl_add_u64 v[4:5], v[4:5], 0, v[20:21]
	s_cmpk_gt_i32 s8, 0x17f
	global_store_short v[4:5], v6, off
	s_cbranch_scc0 .LBB0_1747

.LBB0_2285:
	s_or_b64 exec, exec, s[0:1]
	v_readlane_b32 s0, v253, 0
	v_readlane_b32 s1, v253, 1
	s_waitcnt lgkmcnt(0)
	s_barrier
	s_load_dwordx4 s[24:27], s[0:1], 0xf8
	v_readlane_b32 s8, v253, 61
	v_readlane_b32 s9, v253, 62
	s_mov_b64 s[6:7], -1
	s_and_b64 vcc, exec, s[8:9]
	s_cbranch_vccz .LBB0_2592
	s_load_dwordx2 s[6:7], s[0:1], 0x18
	s_load_dwordx4 s[28:31], s[0:1], 0x20
	v_mov_b32_e32 v1, v0
	v_readlane_b32 s0, v254, 0
	s_lshl_b64 s[22:23], s[36:37], 2
	s_waitcnt lgkmcnt(0)
	s_add_u32 s6, s6, s22
	v_add_u32_e32 v1, s0, v1
	s_movk_i32 s0, 0x1800
	s_addc_u32 s7, s7, s23
	v_lshrrev_b32_e32 v174, 12, v1
	v_and_b32_e32 v175, 0x1ff, v1
	v_lshl_or_b32 v174, v174, 9, v175
	v_lshlrev_b32_e32 v175, 7, v174
	v_add_u32_e32 v176, 0x80000, v175
	v_add_u32_e32 v177, 0x100000, v175
	v_min_u32_e32 v177, 0x167f80, v177
	global_load_dword v178, v175, s[6:7]
	global_load_dword v179, v176, s[6:7]
	global_load_dword v180, v177, s[6:7]
	v_cmp_gt_i32_e32 vcc, s0, v1
	s_and_saveexec_b64 s[36:37], vcc
	s_cbranch_execz .LBB0_2531
	s_add_u32 s38, s26, 0x7c7dc00
	s_addc_u32 s39, s27, 0
	s_add_u32 s40, s26, 0x9cfdc00
	v_lshlrev_b32_e32 v3, 3, v1
	v_readlane_b32 s0, v253, 4
	v_mov_b32_e32 v4, 0
	s_addc_u32 s41, s27, 0
	s_lshl_b32 s42, s0, 3
	s_mov_b64 s[0:1], 0
	v_mov_b32_e32 v20, v3
	v_mov_b32_e32 v21, v1
	v_mov_b32_e32 v5, v4
	v_mov_b32_e32 v6, v4
	v_mov_b32_e32 v7, v4
	v_mov_b32_e32 v8, v4
	v_mov_b32_e32 v9, v4
	v_mov_b32_e32 v10, v4
	v_mov_b32_e32 v11, v4
	s_branch .LBB0_2290

.LBB0_3049:
	s_ashr_i32 s9, s8, 31
	s_lshl_b64 s[16:17], s[8:9], 17
	s_add_u32 s20, s54, s16
	s_addc_u32 s21, s55, s17
	s_and_b64 s[16:17], s[24:25], exec
	v_mov_b32_e32 v4, 0
	s_cselect_b32 s1, s21, s15
	s_cselect_b32 s9, s20, s14
	s_mov_b64 s[24:25], 0
	s_mov_b64 s[16:17], -1
	s_mov_b64 s[26:27], 0
	s_waitcnt lgkmcnt(0)
	v_mov_b32_e32 v5, v4
	v_mov_b32_e32 v6, v4
	v_mov_b32_e32 v7, v4
	v_mov_b32_e32 v8, v4
	v_mov_b32_e32 v9, v4
	v_mov_b32_e32 v10, v4
	v_mov_b32_e32 v11, v4
	v_mov_b32_e32 v20, v4
	v_mov_b32_e32 v21, v4
	v_mov_b32_e32 v22, v4
	v_mov_b32_e32 v23, v4
	v_mov_b32_e32 v24, v4
	v_mov_b32_e32 v25, v4
	v_mov_b32_e32 v26, v4
	v_mov_b32_e32 v27, v4
	v_mov_b32_e32 v36, v4
	v_mov_b32_e32 v37, v4
	v_mov_b32_e32 v38, v4
	v_mov_b32_e32 v39, v4
	v_mov_b32_e32 v40, v4
	v_mov_b32_e32 v41, v4
	v_mov_b32_e32 v42, v4
	v_mov_b32_e32 v43, v4
	v_mov_b32_e32 v52, v4
	v_mov_b32_e32 v53, v4
	v_mov_b32_e32 v54, v4
	v_mov_b32_e32 v55, v4
	v_mov_b32_e32 v56, v4
	v_mov_b32_e32 v57, v4
	v_mov_b32_e32 v58, v4
	v_mov_b32_e32 v59, v4
	v_mov_b32_e32 v12, v4
	v_mov_b32_e32 v13, v4
	v_mov_b32_e32 v14, v4
	v_mov_b32_e32 v15, v4
	v_mov_b32_e32 v16, v4
	v_mov_b32_e32 v17, v4
	v_mov_b32_e32 v18, v4
	v_mov_b32_e32 v19, v4
	v_mov_b32_e32 v28, v4
	v_mov_b32_e32 v29, v4
	v_mov_b32_e32 v30, v4
	v_mov_b32_e32 v31, v4
	v_mov_b32_e32 v32, v4
	v_mov_b32_e32 v33, v4
	v_mov_b32_e32 v34, v4
	v_mov_b32_e32 v35, v4
	v_mov_b32_e32 v44, v4
	v_mov_b32_e32 v45, v4
	v_mov_b32_e32 v46, v4
	v_mov_b32_e32 v47, v4
	v_mov_b32_e32 v48, v4
	v_mov_b32_e32 v49, v4
	v_mov_b32_e32 v50, v4
	v_mov_b32_e32 v51, v4
	v_mov_b32_e32 v60, v4
	v_mov_b32_e32 v61, v4
	v_mov_b32_e32 v62, v4
	v_mov_b32_e32 v63, v4
	v_mov_b32_e32 v64, v4
	v_mov_b32_e32 v65, v4
	v_mov_b32_e32 v66, v4
	v_mov_b32_e32 v67, v4
	v_mov_b32_e32 v68, v4
	v_mov_b32_e32 v69, v4
	v_mov_b32_e32 v70, v4
	v_mov_b32_e32 v71, v4
	v_mov_b32_e32 v72, v4
	v_mov_b32_e32 v73, v4
	v_mov_b32_e32 v74, v4
	v_mov_b32_e32 v75, v4
	v_mov_b32_e32 v84, v4
	v_mov_b32_e32 v85, v4
	v_mov_b32_e32 v86, v4
	v_mov_b32_e32 v87, v4
	v_mov_b32_e32 v88, v4
	v_mov_b32_e32 v89, v4
	v_mov_b32_e32 v90, v4
	v_mov_b32_e32 v91, v4
	v_mov_b32_e32 v100, v4
	v_mov_b32_e32 v101, v4
	v_mov_b32_e32 v102, v4
	v_mov_b32_e32 v103, v4
	v_mov_b32_e32 v104, v4
	v_mov_b32_e32 v105, v4
	v_mov_b32_e32 v106, v4
	v_mov_b32_e32 v107, v4
	v_mov_b32_e32 v116, v4
	v_mov_b32_e32 v117, v4
	v_mov_b32_e32 v118, v4
	v_mov_b32_e32 v119, v4
	v_mov_b32_e32 v120, v4
	v_mov_b32_e32 v121, v4
	v_mov_b32_e32 v122, v4
	v_mov_b32_e32 v123, v4
	v_mov_b32_e32 v76, v4
	v_mov_b32_e32 v77, v4
	v_mov_b32_e32 v78, v4
	v_mov_b32_e32 v79, v4
	v_mov_b32_e32 v80, v4
	v_mov_b32_e32 v81, v4
	v_mov_b32_e32 v82, v4
	v_mov_b32_e32 v83, v4
	v_mov_b32_e32 v92, v4
	v_mov_b32_e32 v93, v4
	v_mov_b32_e32 v94, v4
	v_mov_b32_e32 v95, v4
	v_mov_b32_e32 v96, v4
	v_mov_b32_e32 v97, v4
	v_mov_b32_e32 v98, v4
	v_mov_b32_e32 v99, v4
	v_mov_b32_e32 v108, v4
	v_mov_b32_e32 v109, v4
	v_mov_b32_e32 v110, v4
	v_mov_b32_e32 v111, v4
	v_mov_b32_e32 v112, v4
	v_mov_b32_e32 v113, v4
	v_mov_b32_e32 v114, v4
	v_mov_b32_e32 v115, v4
	v_mov_b32_e32 v124, v4
	v_mov_b32_e32 v125, v4
	v_mov_b32_e32 v126, v4
	v_mov_b32_e32 v127, v4
	v_mov_b32_e32 v128, v4
	v_mov_b32_e32 v129, v4
	v_mov_b32_e32 v130, v4
	v_mov_b32_e32 v131, v4
	s_waitcnt vmcnt(0)
.LBB0_3050:
	s_add_u32 s30, s22, s24
	s_addc_u32 s31, s23, s25
	s_add_u32 s40, s30, 0x100
	s_addc_u32 s41, s31, 0
	s_and_b64 s[28:29], s[26:27], exec
	s_cselect_b32 s43, s19, s41
	s_cselect_b32 s42, s18, s40
	s_add_u32 s24, s14, s24
	s_addc_u32 s25, s15, s25
	s_add_u32 s28, s24, 0x100
	s_addc_u32 s29, s25, 0
	s_add_u32 s24, s42, 0x80
	s_addc_u32 s25, s43, 0
	s_and_b64 s[26:27], s[26:27], exec
	s_cselect_b32 s45, s1, s29
	s_cselect_b32 s44, s9, s28
	s_add_u32 s46, s30, 0x12080
	s_addc_u32 s47, s31, 0
	s_add_i32 s95, s84, s57
	s_add_i32 m0, s63, 0xc000
	s_add_i32 s97, s63, 0xe000
	s_add_i32 s94, s95, 0x2000
	s_add_u32 s40, s44, 0x10000
	s_addc_u32 s41, s45, 0
	s_add_i32 s93, s85, s57
	s_add_i32 s92, s93, 0x2000
	v_add_u32_e32 v152, s84, v1
	s_add_u32 s30, s42, 0x12000
	ds_read_b128 v[140:143], v152
	ds_read_b128 v[144:147], v152 offset:1024
	ds_read_b128 v[148:151], v152 offset:2048
	ds_read_b128 v[152:155], v152 offset:3072
	s_addc_u32 s31, s43, 0
	s_add_u32 s28, s44, 0x80
	s_addc_u32 s29, s45, 0
	s_add_i32 s91, s88, s57
	s_add_i32 s90, s91, 0x2000
	s_add_u32 s26, s44, 0x10080
	s_addc_u32 s27, s45, 0
	s_add_i32 s87, s89, s57
	s_add_i32 s86, s87, 0x2000
	ds_read_b128 v[156:159], v3
	ds_read_b128 v[160:163], v3 offset:1024
	ds_read_b128 v[164:167], v3 offset:2048
	ds_read_b128 v[168:171], v3 offset:3072
	ds_read_b128 v[172:175], v3 offset:4096
	ds_read_b128 v[176:179], v3 offset:5120
	ds_read_b128 v[180:183], v3 offset:6144
	ds_read_b128 v[184:187], v3 offset:7168
	s_nop 0
	v_lshl_add_u64 v[188:189], s[46:47], 0, v[132:133]
	global_load_lds_dwordx4 v[188:189], off
	v_lshl_add_u64 v[188:189], s[46:47], 0, v[136:137]
	s_mov_b32 m0, s97
	s_nop 0
	global_load_lds_dwordx4 v[188:189], off
	s_waitcnt lgkmcnt(8)
	s_barrier
	s_waitcnt lgkmcnt(0)
	s_setprio 1
	s_waitcnt lgkmcnt(0)
	v_mfma_f32_16x16x32_bf16 v[128:131], v[140:143], v[156:159], v[128:131]
	v_mfma_f32_16x16x32_bf16 v[124:127], v[148:151], v[156:159], v[124:127]
	v_mfma_f32_16x16x32_bf16 v[112:115], v[140:143], v[164:167], v[112:115]
	v_mfma_f32_16x16x32_bf16 v[108:111], v[148:151], v[164:167], v[108:111]
	v_mfma_f32_16x16x32_bf16 v[96:99], v[140:143], v[172:175], v[96:99]
	v_mfma_f32_16x16x32_bf16 v[92:95], v[148:151], v[172:175], v[92:95]
	v_mfma_f32_16x16x32_bf16 v[80:83], v[140:143], v[180:183], v[80:83]
	v_mfma_f32_16x16x32_bf16 v[76:79], v[148:151], v[180:183], v[76:79]
	v_mfma_f32_16x16x32_bf16 v[128:131], v[144:147], v[160:163], v[128:131]
	v_mfma_f32_16x16x32_bf16 v[124:127], v[152:155], v[160:163], v[124:127]
	v_mfma_f32_16x16x32_bf16 v[112:115], v[144:147], v[168:171], v[112:115]
	v_mfma_f32_16x16x32_bf16 v[108:111], v[152:155], v[168:171], v[108:111]
	v_mfma_f32_16x16x32_bf16 v[96:99], v[144:147], v[176:179], v[96:99]
	v_mfma_f32_16x16x32_bf16 v[92:95], v[152:155], v[176:179], v[92:95]
	v_mfma_f32_16x16x32_bf16 v[80:83], v[144:147], v[184:187], v[80:83]
	v_mfma_f32_16x16x32_bf16 v[76:79], v[152:155], v[184:187], v[76:79]
	s_setprio 0
	s_barrier
	v_add_u32_e32 v196, s85, v1
	s_mov_b32 m0, s95
	ds_read_b128 v[188:191], v196
	ds_read_b128 v[192:195], v196 offset:1024
	ds_read_b128 v[210:213], v196 offset:2048
	ds_read_b128 v[214:217], v196 offset:3072
	s_nop 0
	v_lshl_add_u64 v[218:219], s[44:45], 0, v[134:135]
	global_load_lds_dwordx4 v[218:219], off
	v_lshl_add_u64 v[218:219], s[44:45], 0, v[138:139]
	s_mov_b32 m0, s94
	s_nop 0
	global_load_lds_dwordx4 v[218:219], off
	s_barrier
	s_waitcnt lgkmcnt(0)
	s_setprio 1
	s_waitcnt lgkmcnt(0)
	v_mfma_f32_16x16x32_bf16 v[120:123], v[188:191], v[156:159], v[120:123]
	v_mfma_f32_16x16x32_bf16 v[116:119], v[210:213], v[156:159], v[116:119]
	v_mfma_f32_16x16x32_bf16 v[104:107], v[188:191], v[164:167], v[104:107]
	v_mfma_f32_16x16x32_bf16 v[100:103], v[210:213], v[164:167], v[100:103]
	v_mfma_f32_16x16x32_bf16 v[88:91], v[188:191], v[172:175], v[88:91]
	v_mfma_f32_16x16x32_bf16 v[84:87], v[210:213], v[172:175], v[84:87]
	v_mfma_f32_16x16x32_bf16 v[72:75], v[188:191], v[180:183], v[72:75]
	v_mfma_f32_16x16x32_bf16 v[68:71], v[210:213], v[180:183], v[68:71]
	v_mfma_f32_16x16x32_bf16 v[120:123], v[192:195], v[160:163], v[120:123]
	v_mfma_f32_16x16x32_bf16 v[116:119], v[214:217], v[160:163], v[116:119]
	v_mfma_f32_16x16x32_bf16 v[104:107], v[192:195], v[168:171], v[104:107]
	v_mfma_f32_16x16x32_bf16 v[100:103], v[214:217], v[168:171], v[100:103]
	v_mfma_f32_16x16x32_bf16 v[88:91], v[192:195], v[176:179], v[88:91]
	v_mfma_f32_16x16x32_bf16 v[84:87], v[214:217], v[176:179], v[84:87]
	v_mfma_f32_16x16x32_bf16 v[72:75], v[192:195], v[184:187], v[72:75]
	v_mfma_f32_16x16x32_bf16 v[68:71], v[214:217], v[184:187], v[68:71]
	s_setprio 0
	s_mov_b32 m0, s63
	s_barrier
	ds_read_b128 v[156:159], v3 offset:16384
	ds_read_b128 v[160:163], v3 offset:17408
	ds_read_b128 v[164:167], v3 offset:18432
	ds_read_b128 v[168:171], v3 offset:19456
	ds_read_b128 v[172:175], v3 offset:20480
	ds_read_b128 v[176:179], v3 offset:21504
	ds_read_b128 v[180:183], v3 offset:22528
	ds_read_b128 v[184:187], v3 offset:23552
	s_nop 0
	v_lshl_add_u64 v[218:219], s[42:43], 0, v[132:133]
	global_load_lds_dwordx4 v[218:219], off
	v_lshl_add_u64 v[218:219], s[42:43], 0, v[136:137]
	s_mov_b32 m0, s64
	s_nop 0
	global_load_lds_dwordx4 v[218:219], off
	s_barrier
	s_waitcnt lgkmcnt(0)
	s_setprio 1
	s_waitcnt lgkmcnt(0)
	v_mfma_f32_16x16x32_bf16 v[64:67], v[140:143], v[156:159], v[64:67]
	v_mfma_f32_16x16x32_bf16 v[60:63], v[148:151], v[156:159], v[60:63]
	v_mfma_f32_16x16x32_bf16 v[48:51], v[140:143], v[164:167], v[48:51]
	v_mfma_f32_16x16x32_bf16 v[44:47], v[148:151], v[164:167], v[44:47]
	v_mfma_f32_16x16x32_bf16 v[32:35], v[140:143], v[172:175], v[32:35]
	v_mfma_f32_16x16x32_bf16 v[28:31], v[148:151], v[172:175], v[28:31]
	v_mfma_f32_16x16x32_bf16 v[16:19], v[140:143], v[180:183], v[16:19]
	v_mfma_f32_16x16x32_bf16 v[12:15], v[148:151], v[180:183], v[12:15]
	v_mfma_f32_16x16x32_bf16 v[64:67], v[144:147], v[160:163], v[64:67]
	v_mfma_f32_16x16x32_bf16 v[60:63], v[152:155], v[160:163], v[60:63]
	v_mfma_f32_16x16x32_bf16 v[48:51], v[144:147], v[168:171], v[48:51]
	v_mfma_f32_16x16x32_bf16 v[44:47], v[152:155], v[168:171], v[44:47]
	v_mfma_f32_16x16x32_bf16 v[32:35], v[144:147], v[176:179], v[32:35]
	v_mfma_f32_16x16x32_bf16 v[28:31], v[152:155], v[176:179], v[28:31]
	v_mfma_f32_16x16x32_bf16 v[16:19], v[144:147], v[184:187], v[16:19]
	v_mfma_f32_16x16x32_bf16 v[12:15], v[152:155], v[184:187], v[12:15]
	s_setprio 0
	s_barrier
	s_mov_b32 m0, s93
	s_nop 0
	v_lshl_add_u64 v[140:141], s[40:41], 0, v[134:135]
	global_load_lds_dwordx4 v[140:141], off
	v_lshl_add_u64 v[140:141], s[40:41], 0, v[138:139]
	s_mov_b32 m0, s92
	s_nop 0
	global_load_lds_dwordx4 v[140:141], off
	s_waitcnt vmcnt(6)
	s_barrier
	s_setprio 1
	v_mfma_f32_16x16x32_bf16 v[56:59], v[188:191], v[156:159], v[56:59]
	v_mfma_f32_16x16x32_bf16 v[52:55], v[210:213], v[156:159], v[52:55]
	v_mfma_f32_16x16x32_bf16 v[40:43], v[188:191], v[164:167], v[40:43]
	v_mfma_f32_16x16x32_bf16 v[36:39], v[210:213], v[164:167], v[36:39]
	v_mfma_f32_16x16x32_bf16 v[24:27], v[188:191], v[172:175], v[24:27]
	v_mfma_f32_16x16x32_bf16 v[20:23], v[210:213], v[172:175], v[20:23]
	v_mfma_f32_16x16x32_bf16 v[8:11], v[188:191], v[180:183], v[8:11]
	v_mfma_f32_16x16x32_bf16 v[4:7], v[210:213], v[180:183], v[4:7]
	v_mfma_f32_16x16x32_bf16 v[56:59], v[192:195], v[160:163], v[56:59]
	v_mfma_f32_16x16x32_bf16 v[52:55], v[214:217], v[160:163], v[52:55]
	v_mfma_f32_16x16x32_bf16 v[40:43], v[192:195], v[168:171], v[40:43]
	v_mfma_f32_16x16x32_bf16 v[36:39], v[214:217], v[168:171], v[36:39]
	v_mfma_f32_16x16x32_bf16 v[24:27], v[192:195], v[176:179], v[24:27]
	v_mfma_f32_16x16x32_bf16 v[20:23], v[214:217], v[176:179], v[20:23]
	v_mfma_f32_16x16x32_bf16 v[8:11], v[192:195], v[184:187], v[8:11]
	v_mfma_f32_16x16x32_bf16 v[4:7], v[214:217], v[184:187], v[4:7]
	s_setprio 0
	v_add_u32_e32 v152, s88, v1
	s_barrier
	ds_read_b128 v[140:143], v152
	ds_read_b128 v[144:147], v152 offset:1024
	ds_read_b128 v[148:151], v152 offset:2048
	ds_read_b128 v[152:155], v152 offset:3072
	s_mov_b32 m0, s65
	ds_read_b128 v[156:159], v3 offset:32768
	ds_read_b128 v[160:163], v3 offset:33792
	ds_read_b128 v[164:167], v3 offset:34816
	ds_read_b128 v[168:171], v3 offset:35840
	ds_read_b128 v[172:175], v3 offset:36864
	ds_read_b128 v[176:179], v3 offset:37888
	ds_read_b128 v[180:183], v3 offset:38912
	ds_read_b128 v[184:187], v3 offset:39936
	s_nop 0
	v_lshl_add_u64 v[188:189], s[30:31], 0, v[132:133]
	global_load_lds_dwordx4 v[188:189], off
	v_lshl_add_u64 v[188:189], s[30:31], 0, v[136:137]
	s_mov_b32 m0, s67
	s_nop 0
	global_load_lds_dwordx4 v[188:189], off
	s_waitcnt lgkmcnt(8)
	s_barrier
	s_waitcnt lgkmcnt(0)
	s_setprio 1
	s_waitcnt lgkmcnt(0)
	v_mfma_f32_16x16x32_bf16 v[128:131], v[140:143], v[156:159], v[128:131]
	v_mfma_f32_16x16x32_bf16 v[124:127], v[148:151], v[156:159], v[124:127]
	v_mfma_f32_16x16x32_bf16 v[112:115], v[140:143], v[164:167], v[112:115]
	v_mfma_f32_16x16x32_bf16 v[108:111], v[148:151], v[164:167], v[108:111]
	v_mfma_f32_16x16x32_bf16 v[96:99], v[140:143], v[172:175], v[96:99]
	v_mfma_f32_16x16x32_bf16 v[92:95], v[148:151], v[172:175], v[92:95]
	v_mfma_f32_16x16x32_bf16 v[80:83], v[140:143], v[180:183], v[80:83]
	v_mfma_f32_16x16x32_bf16 v[76:79], v[148:151], v[180:183], v[76:79]
	v_mfma_f32_16x16x32_bf16 v[128:131], v[144:147], v[160:163], v[128:131]
	v_mfma_f32_16x16x32_bf16 v[124:127], v[152:155], v[160:163], v[124:127]
	v_mfma_f32_16x16x32_bf16 v[112:115], v[144:147], v[168:171], v[112:115]
	v_mfma_f32_16x16x32_bf16 v[108:111], v[152:155], v[168:171], v[108:111]
	v_mfma_f32_16x16x32_bf16 v[96:99], v[144:147], v[176:179], v[96:99]
	v_mfma_f32_16x16x32_bf16 v[92:95], v[152:155], v[176:179], v[92:95]
	v_mfma_f32_16x16x32_bf16 v[80:83], v[144:147], v[184:187], v[80:83]
	v_mfma_f32_16x16x32_bf16 v[76:79], v[152:155], v[184:187], v[76:79]
	s_setprio 0
	s_barrier
	v_add_u32_e32 v196, s89, v1
	s_mov_b32 m0, s91
	ds_read_b128 v[188:191], v196
	ds_read_b128 v[192:195], v196 offset:1024
	ds_read_b128 v[210:213], v196 offset:2048
	ds_read_b128 v[214:217], v196 offset:3072
	s_nop 0
	v_lshl_add_u64 v[218:219], s[28:29], 0, v[134:135]
	global_load_lds_dwordx4 v[218:219], off
	v_lshl_add_u64 v[218:219], s[28:29], 0, v[138:139]
	s_mov_b32 m0, s90
	s_nop 0
	global_load_lds_dwordx4 v[218:219], off
	s_barrier
	s_waitcnt lgkmcnt(0)
	s_setprio 1
	s_waitcnt lgkmcnt(0)
	v_mfma_f32_16x16x32_bf16 v[120:123], v[188:191], v[156:159], v[120:123]
	v_mfma_f32_16x16x32_bf16 v[116:119], v[210:213], v[156:159], v[116:119]
	v_mfma_f32_16x16x32_bf16 v[104:107], v[188:191], v[164:167], v[104:107]
	v_mfma_f32_16x16x32_bf16 v[100:103], v[210:213], v[164:167], v[100:103]
	v_mfma_f32_16x16x32_bf16 v[88:91], v[188:191], v[172:175], v[88:91]
	v_mfma_f32_16x16x32_bf16 v[84:87], v[210:213], v[172:175], v[84:87]
	v_mfma_f32_16x16x32_bf16 v[72:75], v[188:191], v[180:183], v[72:75]
	v_mfma_f32_16x16x32_bf16 v[68:71], v[210:213], v[180:183], v[68:71]
	v_mfma_f32_16x16x32_bf16 v[120:123], v[192:195], v[160:163], v[120:123]
	v_mfma_f32_16x16x32_bf16 v[116:119], v[214:217], v[160:163], v[116:119]
	v_mfma_f32_16x16x32_bf16 v[104:107], v[192:195], v[168:171], v[104:107]
	v_mfma_f32_16x16x32_bf16 v[100:103], v[214:217], v[168:171], v[100:103]
	v_mfma_f32_16x16x32_bf16 v[88:91], v[192:195], v[176:179], v[88:91]
	v_mfma_f32_16x16x32_bf16 v[84:87], v[214:217], v[176:179], v[84:87]
	v_mfma_f32_16x16x32_bf16 v[72:75], v[192:195], v[184:187], v[72:75]
	v_mfma_f32_16x16x32_bf16 v[68:71], v[214:217], v[184:187], v[68:71]
	s_setprio 0
	s_mov_b32 m0, s75
	s_barrier
	ds_read_b128 v[156:159], v3 offset:49152
	ds_read_b128 v[160:163], v3 offset:50176
	ds_read_b128 v[164:167], v3 offset:51200
	ds_read_b128 v[168:171], v3 offset:52224
	ds_read_b128 v[172:175], v3 offset:53248
	ds_read_b128 v[176:179], v3 offset:54272
	ds_read_b128 v[180:183], v3 offset:55296
	ds_read_b128 v[184:187], v3 offset:56320
	s_nop 0
	v_lshl_add_u64 v[218:219], s[24:25], 0, v[132:133]
	global_load_lds_dwordx4 v[218:219], off
	v_lshl_add_u64 v[218:219], s[24:25], 0, v[136:137]
	s_mov_b32 m0, s78
	s_nop 0
	global_load_lds_dwordx4 v[218:219], off
	s_barrier
	s_waitcnt lgkmcnt(0)
	s_setprio 1
	s_waitcnt lgkmcnt(0)
	v_mfma_f32_16x16x32_bf16 v[64:67], v[140:143], v[156:159], v[64:67]
	v_mfma_f32_16x16x32_bf16 v[60:63], v[148:151], v[156:159], v[60:63]
	v_mfma_f32_16x16x32_bf16 v[48:51], v[140:143], v[164:167], v[48:51]
	v_mfma_f32_16x16x32_bf16 v[44:47], v[148:151], v[164:167], v[44:47]
	v_mfma_f32_16x16x32_bf16 v[32:35], v[140:143], v[172:175], v[32:35]
	v_mfma_f32_16x16x32_bf16 v[28:31], v[148:151], v[172:175], v[28:31]
	v_mfma_f32_16x16x32_bf16 v[16:19], v[140:143], v[180:183], v[16:19]
	v_mfma_f32_16x16x32_bf16 v[12:15], v[148:151], v[180:183], v[12:15]
	v_mfma_f32_16x16x32_bf16 v[64:67], v[144:147], v[160:163], v[64:67]
	v_mfma_f32_16x16x32_bf16 v[60:63], v[152:155], v[160:163], v[60:63]
	v_mfma_f32_16x16x32_bf16 v[48:51], v[144:147], v[168:171], v[48:51]
	v_mfma_f32_16x16x32_bf16 v[44:47], v[152:155], v[168:171], v[44:47]
	v_mfma_f32_16x16x32_bf16 v[32:35], v[144:147], v[176:179], v[32:35]
	v_mfma_f32_16x16x32_bf16 v[28:31], v[152:155], v[176:179], v[28:31]
	v_mfma_f32_16x16x32_bf16 v[16:19], v[144:147], v[184:187], v[16:19]
	v_mfma_f32_16x16x32_bf16 v[12:15], v[152:155], v[184:187], v[12:15]
	s_setprio 0
	s_barrier
	s_mov_b32 m0, s87
	s_nop 0
	v_lshl_add_u64 v[140:141], s[26:27], 0, v[134:135]
	global_load_lds_dwordx4 v[140:141], off
	v_lshl_add_u64 v[140:141], s[26:27], 0, v[138:139]
	s_mov_b32 m0, s86
	s_nop 0
	global_load_lds_dwordx4 v[140:141], off
	s_waitcnt vmcnt(6)
	s_barrier
	s_setprio 1
	v_mfma_f32_16x16x32_bf16 v[56:59], v[188:191], v[156:159], v[56:59]
	v_mfma_f32_16x16x32_bf16 v[52:55], v[210:213], v[156:159], v[52:55]
	v_mfma_f32_16x16x32_bf16 v[40:43], v[188:191], v[164:167], v[40:43]
	v_mfma_f32_16x16x32_bf16 v[36:39], v[210:213], v[164:167], v[36:39]
	v_mfma_f32_16x16x32_bf16 v[24:27], v[188:191], v[172:175], v[24:27]
	v_mfma_f32_16x16x32_bf16 v[20:23], v[210:213], v[172:175], v[20:23]
	v_mfma_f32_16x16x32_bf16 v[8:11], v[188:191], v[180:183], v[8:11]
	v_mfma_f32_16x16x32_bf16 v[4:7], v[210:213], v[180:183], v[4:7]
	v_mfma_f32_16x16x32_bf16 v[56:59], v[192:195], v[160:163], v[56:59]
	v_mfma_f32_16x16x32_bf16 v[52:55], v[214:217], v[160:163], v[52:55]
	v_mfma_f32_16x16x32_bf16 v[40:43], v[192:195], v[168:171], v[40:43]
	v_mfma_f32_16x16x32_bf16 v[36:39], v[214:217], v[168:171], v[36:39]
	v_mfma_f32_16x16x32_bf16 v[24:27], v[192:195], v[176:179], v[24:27]
	v_mfma_f32_16x16x32_bf16 v[20:23], v[214:217], v[176:179], v[20:23]
	v_mfma_f32_16x16x32_bf16 v[8:11], v[192:195], v[184:187], v[8:11]
	v_mfma_f32_16x16x32_bf16 v[4:7], v[214:217], v[184:187], v[4:7]
	s_setprio 0
	s_andn2_b64 vcc, exec, s[16:17]
	s_mov_b64 s[26:27], -1
	s_mov_b64 s[16:17], 0
	s_mov_b64 s[24:25], 0x100
	s_barrier
	s_cbranch_vccz .LBB0_3050
	v_mov_b32_e32 v141, v0
	s_ashr_i32 s1, s0, 31
	v_readfirstlane_b32 s9, v141
	s_bfe_u32 s24, s9, 0x20006
	s_ashr_i32 s9, s9, 2
	s_and_b32 s14, s9, 0xffffffc0
	s_ashr_i32 s15, s14, 31
	s_lshl_b64 s[16:17], s[0:1], 10
	s_add_u32 s9, s68, s16
	s_addc_u32 s23, s72, s17
	s_lshl_b64 s[16:17], s[14:15], 2
	v_and_b32_e32 v142, 15, v141
	s_add_u32 s22, s9, s16
	s_addc_u32 s23, s23, s17
	v_lshlrev_b32_e32 v140, 2, v142
	global_load_dword v150, v140, s[22:23] offset:64
	global_load_dword v149, v140, s[22:23] offset:128
	global_load_dword v148, v140, s[22:23] offset:192
	global_load_dword v147, v140, s[22:23] offset:512
	global_load_dword v146, v140, s[22:23] offset:576
	global_load_dword v145, v140, s[22:23] offset:640
	global_load_dword v144, v140, s[22:23] offset:704
	v_mul_f32_e32 v129, v129, v129
	v_mul_f32_e32 v125, v125, v125
	v_mul_f32_e32 v121, v121, v121
	v_mul_f32_e32 v117, v117, v117
	v_fmac_f32_e32 v129, v128, v128
	v_mul_f32_e32 v128, v131, v131
	v_fmac_f32_e32 v125, v124, v124
	v_mul_f32_e32 v124, v127, v127
	v_fmac_f32_e32 v121, v120, v120
	v_mul_f32_e32 v120, v123, v123
	v_fmac_f32_e32 v117, v116, v116
	v_mul_f32_e32 v116, v119, v119
	v_fmac_f32_e32 v128, v130, v130
	v_fmac_f32_e32 v124, v126, v126
	v_fmac_f32_e32 v120, v122, v122
	v_fmac_f32_e32 v116, v118, v118
	v_add_f32_e32 v128, v129, v128
	v_add_f32_e32 v124, v125, v124
	v_add_f32_e32 v120, v121, v120
	v_add_f32_e32 v116, v117, v116
	v_add_f32_e32 v124, v128, v124
	v_add_f32_e32 v116, v120, v116
	v_add_f32_e32 v117, v124, v116
	ds_swizzle_b32 v118, v117 offset:swizzle(SWAP,16)
	v_and_b32_e32 v152, 64, v236
	v_xor_b32_e32 v151, 32, v236
	v_add_u32_e32 v152, 64, v152
	v_cmp_lt_i32_e32 vcc, v151, v152
	s_lshl_b32 s9, s83, 2
	s_or_b32 s24, s24, s9
	v_cndmask_b32_e32 v116, v236, v151, vcc
	s_lshl_b64 s[0:1], s[0:1], 8
	v_lshlrev_b32_e32 v116, 2, v116
	s_waitcnt lgkmcnt(0)
	v_add_f32_e32 v117, v117, v118
	s_add_u32 s0, s0, s14
	ds_bpermute_b32 v118, v116, v117
	s_addc_u32 s1, s1, s15
	s_ashr_i32 s25, s24, 31
	v_or_b32_e32 v143, s0, v142
	v_mov_b32_e32 v142, s1
	s_lshl_b64 s[0:1], s[24:25], 2
	v_and_b32_e32 v119, 48, v141
	s_add_u32 s0, s73, s0
	v_cmp_eq_u32_e64 s[16:17], 0, v119
	s_addc_u32 s1, s74, s1
	s_and_saveexec_b64 s[14:15], s[16:17]
	s_cbranch_execz .LBB0_3053
	v_mov_b32_e32 v141, v2
	v_lshl_add_u64 v[120:121], s[22:23], 0, v[140:141]
	global_load_dword v119, v[120:121], off
	s_waitcnt lgkmcnt(0)
	v_add_f32_e32 v117, v117, v118
	s_waitcnt vmcnt(0)
	v_add_f32_e32 v117, v117, v119
	v_fmamk_f32 v117, v117, 0x3c2aaaab, v231
	v_cmp_gt_f32_e32 vcc, s11, v117
	v_mul_f32_e32 v118, 0x4b800000, v117
	s_nop 0
	v_cndmask_b32_e32 v117, v117, v118, vcc
	v_rsq_f32_e32 v117, v117
	s_nop 0
	v_mul_f32_e32 v118, 0x45800000, v117
	v_cndmask_b32_e32 v117, v117, v118, vcc
	v_mad_u64_u32 v[118:119], s[22:23], v143, 48, s[0:1]
	v_mov_b32_e32 v120, v119
	v_mad_u64_u32 v[120:121], s[22:23], v142, 48, v[120:121]
	v_mov_b32_e32 v119, v120
	global_store_dword v[118:119], v117, off
